# v15 plus projection K loops with the x operand in a 3-slot LDS ring (x DMA two K steps ahead, W one step; LDS 160 KB)
# speedup vs baseline: 1.0499x; 1.0036x over previous
.LBB0_126:
	v_writelane_b32 v254, s52, 25
	s_nop 1
	v_writelane_b32 v254, s53, 26
	v_writelane_b32 v254, s54, 27
	v_writelane_b32 v254, s55, 28
	v_writelane_b32 v254, s56, 29
	v_writelane_b32 v254, s57, 30
	v_writelane_b32 v254, s58, 31
	v_writelane_b32 v254, s59, 32
	v_writelane_b32 v254, s60, 33
	v_writelane_b32 v254, s61, 34
	v_writelane_b32 v254, s62, 35
	v_writelane_b32 v254, s63, 36
	v_writelane_b32 v254, s64, 37
	v_writelane_b32 v254, s65, 38
	v_writelane_b32 v254, s66, 39
	v_writelane_b32 v254, s67, 40
	s_or_b64 exec, exec, s[0:1]
	v_mov_b32_e32 v144, v178
	s_mov_b64 s[0:1], 0
	v_readlane_b32 s2, v254, 0
	s_waitcnt lgkmcnt(0)
	s_barrier
	v_readlane_b32 s3, v254, 1
	s_add_u32 s21, s2, s0
	s_addc_u32 s33, s3, s1
	s_cmpk_lt_i32 s88, 0x440
	s_cselect_b64 s[2:3], -1, 0
	v_writelane_b32 v254, s2, 41
	s_cmpk_gt_i32 s88, 0x43f
	s_nop 0
	v_writelane_b32 v254, s3, 42
	s_cbranch_scc1 .LBB0_179
	s_add_u32 s41, s21, 0xa120000
	s_addc_u32 s49, s33, 0
	s_add_u32 s2, s21, 0x14920000
	v_and_b32_e32 v0, 63, v144
	v_lshlrev_b32_e32 v3, 8, v144
	v_lshlrev_b32_e32 v4, 4, v144
	s_movk_i32 s4, 0x70
	s_addc_u32 s3, s33, 0
	v_and_b32_e32 v3, 0x3800, v3
	v_bitop3_b32 v0, v0, s4, v4 bitop3:0x48
	s_add_u32 s6, s21, 0x1ad20000
	v_and_b32_e32 v1, 31, v144
	v_bfe_u32 v2, v144, 5, 1
	v_or_b32_e32 v145, v0, v3
	v_bitop3_b32 v185, v0, 64, v3 bitop3:0x36
	v_lshrrev_b32_e32 v0, 1, v144
	s_mov_b32 s4, 0x1ffff80
	s_addc_u32 s7, s33, 0
	v_bfe_u32 v3, v144, 1, 3
	v_and_or_b32 v1, v0, s4, v1
	v_bitop3_b32 v0, v2, v0, 7 bitop3:0x78
	s_add_u32 s8, s21, 0x1ada0000
	v_lshlrev_b32_e32 v188, 4, v0
	v_bitop3_b32 v0, v2, v3, 2 bitop3:0x36
	s_addc_u32 s9, s33, 0
	v_lshlrev_b32_e32 v189, 4, v0
	v_bitop3_b32 v0, v2, v3, 4 bitop3:0x36
	s_add_u32 s10, s21, 0x1ade0000
	v_lshlrev_b32_e32 v190, 4, v0
	v_bitop3_b32 v0, v2, v3, 6 bitop3:0x36
	s_addc_u32 s11, s33, 0
	v_lshlrev_b32_e32 v191, 4, v0
	v_and_b32_e32 v0, 64, v179
	s_lshl_b32 s60, s90, 3
	v_readlane_b32 s4, v254, 0
	v_add_u32_e32 v0, 64, v0
	v_readlane_b32 s5, v254, 1
	s_add_u32 s0, s4, s0
	v_lshlrev_b32_e32 v186, 7, v1
	v_lshlrev_b32_e32 v1, 7, v144
	v_cmp_lt_i32_e32 vcc, v184, v0
	s_addc_u32 s1, s5, s1
	v_and_b32_e32 v187, 0x6f80, v1
	v_cndmask_b32_e32 v1, v179, v184, vcc
	v_cmp_lt_i32_e32 vcc, v183, v0
	s_add_u32 s12, s0, 0xc120008
	v_lshlrev_b32_e32 v192, 2, v1
	v_cndmask_b32_e32 v1, v179, v183, vcc
	v_cmp_lt_i32_e32 vcc, v182, v0
	s_addc_u32 s13, s1, 0
	s_lshl_b32 s61, s88, 2
	s_lshl_b32 s62, s90, 2
	v_cndmask_b32_e32 v0, v179, v182, vcc
	s_add_u32 s14, s0, 0xc120108
	s_movk_i32 s18, 0xde00
	v_lshlrev_b32_e32 v193, 2, v1
	v_lshlrev_b32_e32 v194, 2, v0
	s_addc_u32 s15, s1, 0
	s_mov_b32 s17, 0
	s_movk_i32 s63, 0x410
	s_movk_i32 s64, 0x100
	v_mov_b32_e32 v147, 0
	s_mov_b32 s19, -1
	v_mov_b32_e32 v195, 0x358637bd
	s_mov_b32 s65, 0x800000
	s_movk_i32 s66, 0x2200
	s_mov_b32 s20, 0x3e000000
	s_mov_b64 s[22:23], 0x44000
	v_mov_b32_e32 v196, 0x20800
	v_readlane_b32 s67, v254, 22
	s_mov_b32 s80, 0
	s_mov_b32 s56, 0
	s_mov_b32 s57, 0x20000
	v_mov_b32_e32 v194, 0x24000
	ds_read_b32 v198, v194
	ds_read_b32 v199, v194 offset:4
	s_waitcnt lgkmcnt(0)
	v_readfirstlane_b32 s74, v198
	v_readfirstlane_b32 s75, v199
	s_nop 3
	v_writelane_b32 v255, s74, 50
	v_writelane_b32 v255, s75, 51
	s_mov_b32 s68, s88
	s_branch .LBB0_129

.LBB0_130:
	v_add_u32_e32 v164, v168, v189
	v_add_u32_e32 v169, v146, v189
	s_waitcnt lgkmcnt(2)
	v_mfma_f32_32x32x16_bf16 v[0:15], v[128:131], v[132:135], v[0:15]
	ds_read_b128 v[156:159], v164
	s_add_u32 s0, s0, 0x80
	s_addc_u32 s1, s1, 0
	s_add_i32 s47, s47, 1
	s_cmpk_lg_i32 s0, 0x800
	s_mov_b32 s48, s52
	v_mfma_f32_32x32x16_bf16 v[16:31], v[152:155], v[132:135], v[16:31]
	ds_read_b128 v[132:135], v164 offset:4096
	s_waitcnt lgkmcnt(4)
	v_mfma_f32_32x32x16_bf16 v[32:47], v[128:131], v[136:139], v[32:47]
	ds_read_b128 v[160:163], v164 offset:8192
	v_mfma_f32_32x32x16_bf16 v[48:63], v[152:155], v[136:139], v[48:63]
	ds_read_b128 v[136:139], v164 offset:12288
	s_waitcnt lgkmcnt(5)
	v_mfma_f32_32x32x16_bf16 v[64:79], v[128:131], v[140:143], v[64:79]
	ds_read_b128 v[164:167], v169 offset:32768
	v_mfma_f32_32x32x16_bf16 v[80:95], v[152:155], v[140:143], v[80:95]
	ds_read_b128 v[140:143], v169 offset:36864
	v_add_u32_e32 v169, v168, v190
	s_waitcnt lgkmcnt(6)
	v_mfma_f32_32x32x16_bf16 v[96:111], v[128:131], v[148:151], v[96:111]
	v_mfma_f32_32x32x16_bf16 v[112:127], v[152:155], v[148:151], v[112:127]
	s_waitcnt lgkmcnt(1)
	v_mfma_f32_32x32x16_bf16 v[0:15], v[164:167], v[156:159], v[0:15]
	ds_read_b128 v[128:131], v169
	s_waitcnt lgkmcnt(1)
	v_mfma_f32_32x32x16_bf16 v[16:31], v[140:143], v[156:159], v[16:31]
	ds_read_b128 v[148:151], v169 offset:4096
	v_mfma_f32_32x32x16_bf16 v[32:47], v[164:167], v[132:135], v[32:47]
	ds_read_b128 v[152:155], v169 offset:8192
	v_mfma_f32_32x32x16_bf16 v[48:63], v[140:143], v[132:135], v[48:63]
	ds_read_b128 v[132:135], v169 offset:12288
	v_add_u32_e32 v169, v146, v190
	v_add_u32_e32 v146, v146, v191
	v_mfma_f32_32x32x16_bf16 v[64:79], v[164:167], v[160:163], v[64:79]
	ds_read_b128 v[156:159], v169 offset:32768
	v_mfma_f32_32x32x16_bf16 v[80:95], v[140:143], v[160:163], v[80:95]
	ds_read_b128 v[160:163], v169 offset:36864
	v_mfma_f32_32x32x16_bf16 v[96:111], v[164:167], v[136:139], v[96:111]
	v_add_u32_e32 v164, v168, v191
	v_mfma_f32_32x32x16_bf16 v[112:127], v[140:143], v[136:139], v[112:127]
	s_waitcnt lgkmcnt(1)
	v_mfma_f32_32x32x16_bf16 v[0:15], v[156:159], v[128:131], v[0:15]
	ds_read_b128 v[136:139], v164
	s_waitcnt lgkmcnt(1)
	v_mfma_f32_32x32x16_bf16 v[16:31], v[160:163], v[128:131], v[16:31]
	ds_read_b128 v[128:131], v164 offset:4096
	v_mfma_f32_32x32x16_bf16 v[32:47], v[156:159], v[148:151], v[32:47]
	ds_read_b128 v[140:143], v164 offset:8192
	v_mfma_f32_32x32x16_bf16 v[48:63], v[160:163], v[148:151], v[48:63]
	ds_read_b128 v[148:151], v164 offset:12288
	v_mfma_f32_32x32x16_bf16 v[64:79], v[156:159], v[152:155], v[64:79]
	ds_read_b128 v[164:167], v146 offset:32768
	v_mfma_f32_32x32x16_bf16 v[80:95], v[160:163], v[152:155], v[80:95]
	ds_read_b128 v[152:155], v146 offset:36864
	v_mfma_f32_32x32x16_bf16 v[96:111], v[156:159], v[132:135], v[96:111]
	v_mfma_f32_32x32x16_bf16 v[112:127], v[160:163], v[132:135], v[112:127]
	s_waitcnt lgkmcnt(0)
	s_cbranch_scc0 .Lxt_L0
	s_cmp_lt_u32 s47, 15
	s_cbranch_scc0 .Lxr_w0_L0
	s_waitcnt vmcnt(4)
	s_branch .Lxr_wb_L0

.Lxr_wb_L0:
	s_barrier
	s_and_b32 s4, s48, 0x10000
	v_or_b32_e32 v146, s4, v187
	v_add_u32_e32 v194, v146, v188
	v_add_u32_e32 v168, s56, v186
	v_add_u32_e32 v195, v168, v188
	ds_read_b128 v[132:135], v195
	v_mfma_f32_32x32x16_bf16 v[16:31], v[152:155], v[136:139], v[16:31]
	v_mfma_f32_32x32x16_bf16 v[48:63], v[152:155], v[128:131], v[48:63]
	v_mfma_f32_32x32x16_bf16 v[80:95], v[152:155], v[140:143], v[80:95]
	v_mfma_f32_32x32x16_bf16 v[112:127], v[152:155], v[148:151], v[112:127]
	ds_read_b128 v[152:155], v194 offset:36864
	v_mfma_f32_32x32x16_bf16 v[0:15], v[164:167], v[136:139], v[0:15]
	ds_read_b128 v[136:139], v195 offset:4096
	v_mfma_f32_32x32x16_bf16 v[32:47], v[164:167], v[128:131], v[32:47]
	ds_read_b128 v[128:131], v194 offset:32768
	v_mfma_f32_32x32x16_bf16 v[64:79], v[164:167], v[140:143], v[64:79]
	ds_read_b128 v[140:143], v195 offset:8192
	v_mfma_f32_32x32x16_bf16 v[96:111], v[164:167], v[148:151], v[96:111]
	ds_read_b128 v[148:151], v195 offset:12288
	s_add_i32 s52, s48, 0x10000
	s_cmp_lt_u32 s47, 15
	s_cbranch_scc0 .Lxr_ni_L0s
	s_add_u32 s82, s0, s81
	s_addk_i32 s82, 0x80
	s_and_b32 s82, s82, 0x7ff
	s_cmp_eq_u32 s47, 0
	s_cbranch_scc0 .Lxr_n1_L0s
	s_add_u32 s74, s56, s57
	s_sub_u32 s74, 0x30000, s74
	s_add_u32 s74, s74, s26
	s_add_u32 s4, s45, s82
	s_addc_u32 s5, s46, 0
	s_add_u32 s75, s74, 0x0
	s_mov_b32 m0, s75
	global_load_lds_dwordx4 v145, s[4:5]
	s_add_u32 s4, s43, s82
	s_addc_u32 s5, s44, 0
	s_add_u32 s75, s74, 0x400
	s_mov_b32 m0, s75
	global_load_lds_dwordx4 v185, s[4:5]
	s_add_u32 s4, s40, s82
	s_addc_u32 s5, s42, 0
	s_add_u32 s75, s74, 0x800
	s_mov_b32 m0, s75
	global_load_lds_dwordx4 v145, s[4:5]
	s_add_u32 s4, s37, s82
	s_addc_u32 s5, s39, 0
	s_add_u32 s75, s74, 0xc00
	s_mov_b32 m0, s75
	global_load_lds_dwordx4 v185, s[4:5]
.Lxr_n1_L0s:
	s_and_b32 s74, s52, 0x10000
	s_add_u32 s74, s74, s26
	s_add_u32 s74, s74, 0x8000
	s_add_u32 s4, s35, s82
	s_addc_u32 s5, s36, 0
	s_add_u32 s75, s74, 0x0
	s_mov_b32 m0, s75
	global_load_lds_dwordx4 v145, s[4:5]
	s_add_u32 s4, s31, s82
	s_addc_u32 s5, s34, 0
	s_add_u32 s75, s74, 0x400
	s_mov_b32 m0, s75
	global_load_lds_dwordx4 v185, s[4:5]
	s_add_u32 s4, s29, s82
	s_addc_u32 s5, s30, 0
	s_add_u32 s75, s74, 0x800
	s_mov_b32 m0, s75
	global_load_lds_dwordx4 v145, s[4:5]
	s_add_u32 s4, s27, s82
	s_addc_u32 s5, s28, 0
	s_add_u32 s75, s74, 0xc00
	s_mov_b32 m0, s75
	global_load_lds_dwordx4 v185, s[4:5]
	s_cmp_lt_u32 s47, 14
	s_cbranch_scc0 .Lxr_ni_L0s
	s_addk_i32 s82, 0x80
	s_and_b32 s82, s82, 0x7ff
	s_add_u32 s74, s57, s26
	s_add_u32 s4, s45, s82
	s_addc_u32 s5, s46, 0
	s_add_u32 s75, s74, 0x0
	s_mov_b32 m0, s75
	global_load_lds_dwordx4 v145, s[4:5]
	s_add_u32 s4, s43, s82
	s_addc_u32 s5, s44, 0
	s_add_u32 s75, s74, 0x400
	s_mov_b32 m0, s75
	global_load_lds_dwordx4 v185, s[4:5]
	s_add_u32 s4, s40, s82
	s_addc_u32 s5, s42, 0
	s_add_u32 s75, s74, 0x800
	s_mov_b32 m0, s75
	global_load_lds_dwordx4 v145, s[4:5]
	s_add_u32 s4, s37, s82
	s_addc_u32 s5, s39, 0
	s_add_u32 s75, s74, 0xc00
	s_mov_b32 m0, s75
	global_load_lds_dwordx4 v185, s[4:5]
.Lxr_ni_L0s:
	s_add_u32 s74, s56, s57
	s_sub_u32 s74, 0x30000, s74
	s_mov_b32 s57, s56
	s_mov_b32 s56, s74
	s_branch .LBB0_130

.Lkin_L0:
	s_and_b32 s4, s48, 0x10000
	v_or_b32_e32 v146, s4, v187
	v_add_u32_e32 v194, v146, v188
	v_add_u32_e32 v168, s56, v186
	v_add_u32_e32 v195, v168, v188
	ds_read_b128 v[132:135], v195
	ds_read_b128 v[152:155], v194 offset:36864
	ds_read_b128 v[136:139], v195 offset:4096
	ds_read_b128 v[128:131], v194 offset:32768
	ds_read_b128 v[140:143], v195 offset:8192
	ds_read_b128 v[148:151], v195 offset:12288
	s_add_i32 s52, s48, 0x10000
	s_cmp_lt_u32 s47, 15
	s_cbranch_scc0 .Lxr_ni_L0e
	s_add_u32 s82, s0, s81
	s_addk_i32 s82, 0x80
	s_and_b32 s82, s82, 0x7ff
	s_cmp_eq_u32 s47, 0
	s_cbranch_scc0 .Lxr_n1_L0e
	s_add_u32 s74, s56, s57
	s_sub_u32 s74, 0x30000, s74
	s_add_u32 s74, s74, s26
	s_add_u32 s4, s45, s82
	s_addc_u32 s5, s46, 0
	s_add_u32 s75, s74, 0x0
	s_mov_b32 m0, s75
	global_load_lds_dwordx4 v145, s[4:5]
	s_add_u32 s4, s43, s82
	s_addc_u32 s5, s44, 0
	s_add_u32 s75, s74, 0x400
	s_mov_b32 m0, s75
	global_load_lds_dwordx4 v185, s[4:5]
	s_add_u32 s4, s40, s82
	s_addc_u32 s5, s42, 0
	s_add_u32 s75, s74, 0x800
	s_mov_b32 m0, s75
	global_load_lds_dwordx4 v145, s[4:5]
	s_add_u32 s4, s37, s82
	s_addc_u32 s5, s39, 0
	s_add_u32 s75, s74, 0xc00
	s_mov_b32 m0, s75
	global_load_lds_dwordx4 v185, s[4:5]

.Lpe_entry_L0:
	s_nop 7
	s_and_b32 s24, s99, 7
	s_lshl_b32 s24, s24, 3
	s_bfe_u32 s25, s99, 0x30003
	s_or_b32 s24, s24, s25
	s_lshr_b32 s25, s99, 6
	v_readfirstlane_b32 s26, v178
	v_readlane_b32 s72, v254, 0
	v_readlane_b32 s73, v254, 1
	s_lshr_b32 s26, s26, 6
	s_lshr_b32 s27, s26, 2
	s_and_b32 s28, s26, 3
	s_lshl_b32 s29, s24, 8
	s_lshl_b32 s30, s27, 7
	s_add_u32 s29, s29, s30
	s_lshl_b32 s30, s25, 8
	s_lshl_b32 s31, s28, 6
	s_add_u32 s30, s30, s31
	s_lshl_b32 s31, s29, 5
	s_add_u32 s94, s72, 0x1ad20000
	s_addc_u32 s95, s73, 0
	s_add_u32 s94, s94, s31
	s_addc_u32 s95, s95, 0
	v_and_b32_e32 v197, 31, v179
	v_lshrrev_b32_e32 v146, 5, v179
	v_lshlrev_b32_e32 v180, 5, v197
	v_lshlrev_b32_e32 v146, 4, v146
	global_load_dwordx4 v[128:131], v180, s[94:95] offset:0
	global_load_dwordx4 v[132:135], v180, s[94:95] offset:16
	global_load_dwordx4 v[136:139], v180, s[94:95] offset:1024
	global_load_dwordx4 v[140:143], v180, s[94:95] offset:1040
	global_load_dwordx4 v[164:167], v180, s[94:95] offset:2048
	global_load_dwordx4 v[168:171], v180, s[94:95] offset:2064
	global_load_dwordx4 v[246:249], v180, s[94:95] offset:3072
	global_load_dwordx4 v[250:253], v180, s[94:95] offset:3088
	s_mul_i32 s31, s29, 0x2200
	s_lshl_b32 s32, s30, 1
	s_add_u32 s31, s31, s32
	s_add_u32 s74, s72, 0xc120000
	s_addc_u32 s75, s73, 0
	s_add_u32 s74, s74, s31
	s_addc_u32 s75, s75, 0
	v_mul_u32_u24_e32 v181, 0x2200, v197
	v_add_u32_e32 v181, v181, v146
	s_sub_u32 s34, s25, 4
	s_cmp_lt_u32 s34, 2
	s_cbranch_scc1 .Lpe_vt_all_L0
	s_cmp_eq_u32 s25, 8
	s_cbranch_scc0 .Lpe_notv_L0
	s_barrier
	s_mov_b32 s56, 0
	s_mov_b32 s57, 0x20000
	s_cmp_ge_u32 s28, 2
	s_cbranch_scc1 .Lpe_vt_L0
	s_branch .Lpe_notv_L0
.Lpe_vt_all_L0:
	s_barrier
	s_mov_b32 s56, 0
	s_mov_b32 s57, 0x20000
	s_branch .Lpe_vt_L0
.Lpe_notv_L0:
	s_cmp_ge_u32 s25, 9
	s_cbranch_scc1 .Lpe_gates_L0
	s_lshr_b32 s34, s25, 1
	s_cmp_ge_u32 s25, 6
	s_cselect_b32 s35, 1, 0
	s_sub_u32 s34, s34, s35
	s_lshl_b32 s35, s98, 2
	s_add_u32 s35, s35, s34
	s_lshl_b32 s35, s35, 8
	v_readlane_b32 s82, v254, 14
	v_readlane_b32 s83, v254, 15
	s_add_u32 s82, s82, s35
	s_addc_u32 s83, s83, 0
	global_load_dwordx4 v[198:201], v146, s[82:83] offset:0
	global_load_dwordx4 v[202:205], v146, s[82:83] offset:32
	global_load_dwordx4 v[206:209], v146, s[82:83] offset:64
	global_load_dwordx4 v[210:213], v146, s[82:83] offset:96
	global_load_dwordx4 v[214:217], v146, s[82:83] offset:128
	global_load_dwordx4 v[218:221], v146, s[82:83] offset:160
	global_load_dwordx4 v[222:225], v146, s[82:83] offset:192
	global_load_dwordx4 v[226:229], v146, s[82:83] offset:224
	s_and_b32 s35, s34, 1
	s_cmp_eq_u32 s35, 0
	s_cselect_b32 s36, 0x3e000000, 1.0
	s_and_b32 s35, s29, 0x7ff
	s_lshl_b32 s35, s35, 7
	s_add_u32 s96, s72, 0x1ada0000
	s_addc_u32 s97, s73, 0
	s_add_u32 s96, s96, s35
	s_addc_u32 s97, s97, 0
	s_add_u32 s100, s96, 0x40000
	s_addc_u32 s101, s97, 0
	s_cmp_ge_u32 s34, 2
	s_cselect_b32 s37, 1, 0
	s_waitcnt vmcnt(8)
	v_lshlrev_b32_e32 v180, 7, v197
	v_add_u32_e32 v180, v180, v146
	v_mov_b32_e32 v197, 0x358637bd
	v_pk_add_f32 v[128:129], v[128:129], v[130:131]
	v_pk_add_f32 v[132:133], v[132:133], v[134:135]
	v_pk_add_f32 v[136:137], v[136:137], v[138:139]
	v_pk_add_f32 v[140:141], v[140:141], v[142:143]
	v_pk_add_f32 v[164:165], v[164:165], v[166:167]
	v_pk_add_f32 v[168:169], v[168:169], v[170:171]
	v_pk_add_f32 v[246:247], v[246:247], v[248:249]
	v_pk_add_f32 v[250:251], v[250:251], v[252:253]
	v_pk_add_f32 v[128:129], v[128:129], v[132:133]
	v_pk_add_f32 v[136:137], v[136:137], v[140:141]
	v_pk_add_f32 v[164:165], v[164:165], v[168:169]
	v_pk_add_f32 v[246:247], v[246:247], v[250:251]
	v_add_f32_e32 v128, v128, v129
	v_add_f32_e32 v136, v136, v137
	v_add_f32_e32 v164, v164, v165
	v_add_f32_e32 v246, v246, v247
	v_fmamk_f32 v128, v128, 0x3a800000, v197
	v_fmamk_f32 v136, v136, 0x3a800000, v197
	v_fmamk_f32 v164, v164, 0x3a800000, v197
	v_fmamk_f32 v246, v246, 0x3a800000, v197
	v_rsq_f32_e32 v172, v128
	v_rsq_f32_e32 v173, v136
	v_rsq_f32_e32 v174, v164
	v_rsq_f32_e32 v175, v246
	s_nop 0
	s_add_u32 s76, s99, s90
	s_cmp_lt_u32 s76, 0x440
	s_cselect_b32 s80, 1, 0
	s_cselect_b32 s83, 0x200000, 0
	s_lshl_b32 s76, s24, 19
	s_lshl_b32 s77, s26, 16
	s_add_u32 s76, s76, s77
	s_and_b32 s77, s24, 7
	s_lshl_b32 s77, s77, 8
	s_add_u32 s76, s76, s77
	s_add_u32 s78, s72, 0xa120000
	s_addc_u32 s79, s73, 0
	s_add_u32 s78, s78, s76
	s_addc_u32 s79, s79, 0
	s_lshl_b32 s76, s25, 19
	s_add_u32 s76, s76, s83
	s_add_u32 s76, s76, s77
	s_lshl_b32 s77, s26, 16
	s_add_u32 s76, s76, s77
	s_add_u32 s82, s72, 0x0
	s_addc_u32 s83, s73, 0
	s_add_u32 s82, s82, s76
	s_addc_u32 s83, s83, 0
	s_lshl_b32 s76, s26, 12
	s_add_u32 s76, s76, s56
	s_mov_b32 m0, s76
	s_nop 0
	global_load_lds_dwordx4 v145, s[78:79]
	s_add_u32 s78, s78, 0x4000
	s_addc_u32 s79, s79, 0
	s_add_u32 s76, s76, 0x400
	s_mov_b32 m0, s76
	s_nop 0
	global_load_lds_dwordx4 v185, s[78:79]
	s_add_u32 s78, s78, 0x4000
	s_addc_u32 s79, s79, 0
	s_add_u32 s76, s76, 0x400
	s_mov_b32 m0, s76
	s_nop 0
	global_load_lds_dwordx4 v145, s[78:79]
	s_add_u32 s78, s78, 0x4000
	s_addc_u32 s79, s79, 0
	s_add_u32 s76, s76, 0x400
	s_mov_b32 m0, s76
	s_nop 0
	global_load_lds_dwordx4 v185, s[78:79]
	s_add_u32 s78, s78, 0x4000
	s_addc_u32 s79, s79, 0
	s_add_u32 s76, s76, 0x400
	s_sub_u32 s76, s76, s56
	s_add_u32 s76, s76, 0x7000
	s_mov_b32 m0, s76
	s_nop 0
	global_load_lds_dwordx4 v145, s[82:83]
	s_add_u32 s82, s82, 0x4000
	s_addc_u32 s83, s83, 0
	s_add_u32 s76, s76, 0x400
	s_mov_b32 m0, s76
	s_nop 0
	global_load_lds_dwordx4 v185, s[82:83]
	s_add_u32 s82, s82, 0x4000
	s_addc_u32 s83, s83, 0
	s_add_u32 s76, s76, 0x400
	s_mov_b32 m0, s76
	s_nop 0
	global_load_lds_dwordx4 v145, s[82:83]
	s_add_u32 s82, s82, 0x4000
	s_addc_u32 s83, s83, 0
	s_add_u32 s76, s76, 0x400
	s_mov_b32 m0, s76
	s_nop 0
	global_load_lds_dwordx4 v185, s[82:83]
	s_add_u32 s82, s82, 0x4000
	s_addc_u32 s83, s83, 0
	s_add_u32 s76, s76, 0x400
	s_cmp_eq_u32 s37, 0
	s_cbranch_scc1 .Lpe_norope_ld_L0
	global_load_dwordx4 v[230:233], v180, s[96:97] offset:0
	global_load_dwordx4 v[234:237], v180, s[96:97] offset:32
	global_load_dwordx4 v[238:241], v180, s[96:97] offset:64
	global_load_dwordx4 v[242:245], v180, s[96:97] offset:96
	global_load_dwordx4 v[148:151], v180, s[100:101] offset:0
	global_load_dwordx4 v[152:155], v180, s[100:101] offset:32
	global_load_dwordx4 v[156:159], v180, s[100:101] offset:64
	global_load_dwordx4 v[160:163], v180, s[100:101] offset:96

.Lpe_gates_L0:
	s_lshl_b32 s35, s98, 11
	s_add_u32 s35, s35, s30
	s_sub_u32 s35, s35, 0x900
	s_lshl_b32 s35, s35, 2
	v_readlane_b32 s82, v254, 12
	v_readlane_b32 s83, v254, 13
	s_add_u32 s82, s82, s35
	s_addc_u32 s83, s83, 0
	global_load_dwordx4 v[198:201], v146, s[82:83] offset:0
	global_load_dwordx4 v[202:205], v146, s[82:83] offset:32
	global_load_dwordx4 v[206:209], v146, s[82:83] offset:64
	global_load_dwordx4 v[210:213], v146, s[82:83] offset:96
	global_load_dwordx4 v[214:217], v146, s[82:83] offset:128
	global_load_dwordx4 v[218:221], v146, s[82:83] offset:160
	global_load_dwordx4 v[222:225], v146, s[82:83] offset:192
	global_load_dwordx4 v[226:229], v146, s[82:83] offset:224
	s_waitcnt vmcnt(8)
	v_mov_b32_e32 v197, 0x358637bd
	v_pk_add_f32 v[128:129], v[128:129], v[130:131]
	v_pk_add_f32 v[132:133], v[132:133], v[134:135]
	v_pk_add_f32 v[136:137], v[136:137], v[138:139]
	v_pk_add_f32 v[140:141], v[140:141], v[142:143]
	v_pk_add_f32 v[164:165], v[164:165], v[166:167]
	v_pk_add_f32 v[168:169], v[168:169], v[170:171]
	v_pk_add_f32 v[246:247], v[246:247], v[248:249]
	v_pk_add_f32 v[250:251], v[250:251], v[252:253]
	v_pk_add_f32 v[128:129], v[128:129], v[132:133]
	v_pk_add_f32 v[136:137], v[136:137], v[140:141]
	v_pk_add_f32 v[164:165], v[164:165], v[168:169]
	v_pk_add_f32 v[246:247], v[246:247], v[250:251]
	v_add_f32_e32 v128, v128, v129
	v_add_f32_e32 v136, v136, v137
	v_add_f32_e32 v164, v164, v165
	v_add_f32_e32 v246, v246, v247
	v_fmamk_f32 v128, v128, 0x3a800000, v197
	v_fmamk_f32 v136, v136, 0x3a800000, v197
	v_fmamk_f32 v164, v164, 0x3a800000, v197
	v_fmamk_f32 v246, v246, 0x3a800000, v197
	v_rsq_f32_e32 v172, v128
	v_rsq_f32_e32 v173, v136
	v_rsq_f32_e32 v174, v164
	v_rsq_f32_e32 v175, v246
	s_nop 0
	s_add_u32 s76, s99, s90
	s_cmp_lt_u32 s76, 0x440
	s_cselect_b32 s80, 1, 0
	s_cselect_b32 s83, 0x200000, 0
	s_lshl_b32 s76, s24, 19
	s_lshl_b32 s77, s26, 16
	s_add_u32 s76, s76, s77
	s_and_b32 s77, s24, 7
	s_lshl_b32 s77, s77, 8
	s_add_u32 s76, s76, s77
	s_add_u32 s78, s72, 0xa120000
	s_addc_u32 s79, s73, 0
	s_add_u32 s78, s78, s76
	s_addc_u32 s79, s79, 0
	s_lshl_b32 s76, s25, 19
	s_add_u32 s76, s76, s83
	s_add_u32 s76, s76, s77
	s_lshl_b32 s77, s26, 16
	s_add_u32 s76, s76, s77
	s_add_u32 s82, s72, 0x0
	s_addc_u32 s83, s73, 0
	s_add_u32 s82, s82, s76
	s_addc_u32 s83, s83, 0
	s_lshl_b32 s76, s26, 12
	s_add_u32 s76, s76, s56
	s_mov_b32 m0, s76
	s_nop 0
	global_load_lds_dwordx4 v145, s[78:79]
	s_add_u32 s78, s78, 0x4000
	s_addc_u32 s79, s79, 0
	s_add_u32 s76, s76, 0x400
	s_mov_b32 m0, s76
	s_nop 0
	global_load_lds_dwordx4 v185, s[78:79]
	s_add_u32 s78, s78, 0x4000
	s_addc_u32 s79, s79, 0
	s_add_u32 s76, s76, 0x400
	s_mov_b32 m0, s76
	s_nop 0
	global_load_lds_dwordx4 v145, s[78:79]
	s_add_u32 s78, s78, 0x4000
	s_addc_u32 s79, s79, 0
	s_add_u32 s76, s76, 0x400
	s_mov_b32 m0, s76
	s_nop 0
	global_load_lds_dwordx4 v185, s[78:79]
	s_add_u32 s78, s78, 0x4000
	s_addc_u32 s79, s79, 0
	s_add_u32 s76, s76, 0x400
	s_sub_u32 s76, s76, s56
	s_add_u32 s76, s76, 0x7000
	s_mov_b32 m0, s76
	s_nop 0
	global_load_lds_dwordx4 v145, s[82:83]
	s_add_u32 s82, s82, 0x4000
	s_addc_u32 s83, s83, 0
	s_add_u32 s76, s76, 0x400
	s_mov_b32 m0, s76
	s_nop 0
	global_load_lds_dwordx4 v185, s[82:83]
	s_add_u32 s82, s82, 0x4000
	s_addc_u32 s83, s83, 0
	s_add_u32 s76, s76, 0x400
	s_mov_b32 m0, s76
	s_nop 0
	global_load_lds_dwordx4 v145, s[82:83]
	s_add_u32 s82, s82, 0x4000
	s_addc_u32 s83, s83, 0
	s_add_u32 s76, s76, 0x400
	s_mov_b32 m0, s76
	s_nop 0
	global_load_lds_dwordx4 v185, s[82:83]
	s_add_u32 s82, s82, 0x4000
	s_addc_u32 s83, s83, 0
	s_add_u32 s76, s76, 0x400
	v_mul_f32_e32 v172, 0xbfb8aa3b, v172
	v_mul_f32_e32 v173, 0xbfb8aa3b, v173
	v_mul_f32_e32 v174, 0xbfb8aa3b, v174
	v_mul_f32_e32 v175, 0xbfb8aa3b, v175
	s_waitcnt vmcnt(8)
	v_mul_f32_e32 v198, 0xbfb8aa3b, v198
	v_mul_f32_e32 v199, 0xbfb8aa3b, v199
	v_mul_f32_e32 v200, 0xbfb8aa3b, v200
	v_mul_f32_e32 v201, 0xbfb8aa3b, v201
	v_mul_f32_e32 v202, 0xbfb8aa3b, v202
	v_mul_f32_e32 v203, 0xbfb8aa3b, v203
	v_mul_f32_e32 v204, 0xbfb8aa3b, v204
	v_mul_f32_e32 v205, 0xbfb8aa3b, v205
	v_mul_f32_e32 v206, 0xbfb8aa3b, v206
	v_mul_f32_e32 v207, 0xbfb8aa3b, v207
	v_mul_f32_e32 v208, 0xbfb8aa3b, v208
	v_mul_f32_e32 v209, 0xbfb8aa3b, v209
	v_mul_f32_e32 v210, 0xbfb8aa3b, v210
	v_mul_f32_e32 v211, 0xbfb8aa3b, v211
	v_mul_f32_e32 v212, 0xbfb8aa3b, v212
	v_mul_f32_e32 v213, 0xbfb8aa3b, v213
	v_mul_f32_e32 v214, 0xbfb8aa3b, v214
	v_mul_f32_e32 v215, 0xbfb8aa3b, v215
	v_mul_f32_e32 v216, 0xbfb8aa3b, v216
	v_mul_f32_e32 v217, 0xbfb8aa3b, v217
	v_mul_f32_e32 v218, 0xbfb8aa3b, v218
	v_mul_f32_e32 v219, 0xbfb8aa3b, v219
	v_mul_f32_e32 v220, 0xbfb8aa3b, v220
	v_mul_f32_e32 v221, 0xbfb8aa3b, v221
	v_mul_f32_e32 v222, 0xbfb8aa3b, v222
	v_mul_f32_e32 v223, 0xbfb8aa3b, v223
	v_mul_f32_e32 v224, 0xbfb8aa3b, v224
	v_mul_f32_e32 v225, 0xbfb8aa3b, v225
	v_mul_f32_e32 v226, 0xbfb8aa3b, v226
	v_mul_f32_e32 v227, 0xbfb8aa3b, v227
	v_mul_f32_e32 v228, 0xbfb8aa3b, v228
	v_mul_f32_e32 v229, 0xbfb8aa3b, v229
	v_pk_fma_f32 v[0:1], v[0:1], v[172:173], v[198:199] op_sel_hi:[1,0,1]
	v_pk_fma_f32 v[2:3], v[2:3], v[172:173], v[200:201] op_sel_hi:[1,0,1]
	v_pk_fma_f32 v[4:5], v[4:5], v[172:173], v[202:203] op_sel_hi:[1,0,1]
	v_pk_fma_f32 v[6:7], v[6:7], v[172:173], v[204:205] op_sel_hi:[1,0,1]
	v_pk_fma_f32 v[8:9], v[8:9], v[172:173], v[206:207] op_sel_hi:[1,0,1]
	v_pk_fma_f32 v[10:11], v[10:11], v[172:173], v[208:209] op_sel_hi:[1,0,1]
	v_pk_fma_f32 v[12:13], v[12:13], v[172:173], v[210:211] op_sel_hi:[1,0,1]
	v_pk_fma_f32 v[14:15], v[14:15], v[172:173], v[212:213] op_sel_hi:[1,0,1]
	v_pk_fma_f32 v[16:17], v[16:17], v[172:173], v[214:215] op_sel_hi:[1,0,1]
	v_pk_fma_f32 v[18:19], v[18:19], v[172:173], v[216:217] op_sel_hi:[1,0,1]
	v_pk_fma_f32 v[20:21], v[20:21], v[172:173], v[218:219] op_sel_hi:[1,0,1]
	v_pk_fma_f32 v[22:23], v[22:23], v[172:173], v[220:221] op_sel_hi:[1,0,1]
	v_pk_fma_f32 v[24:25], v[24:25], v[172:173], v[222:223] op_sel_hi:[1,0,1]
	v_pk_fma_f32 v[26:27], v[26:27], v[172:173], v[224:225] op_sel_hi:[1,0,1]
	v_pk_fma_f32 v[28:29], v[28:29], v[172:173], v[226:227] op_sel_hi:[1,0,1]
	v_pk_fma_f32 v[30:31], v[30:31], v[172:173], v[228:229] op_sel_hi:[1,0,1]
	v_exp_f32_e32 v0, v0
	v_exp_f32_e32 v1, v1
	v_exp_f32_e32 v2, v2
	v_exp_f32_e32 v3, v3
	v_exp_f32_e32 v4, v4
	v_exp_f32_e32 v5, v5
	v_exp_f32_e32 v6, v6
	v_exp_f32_e32 v7, v7
	v_exp_f32_e32 v8, v8
	v_exp_f32_e32 v9, v9
	v_exp_f32_e32 v10, v10
	v_exp_f32_e32 v11, v11
	v_exp_f32_e32 v12, v12
	v_exp_f32_e32 v13, v13
	v_exp_f32_e32 v14, v14
	v_exp_f32_e32 v15, v15
	v_exp_f32_e32 v16, v16
	v_exp_f32_e32 v17, v17
	v_exp_f32_e32 v18, v18
	v_exp_f32_e32 v19, v19
	v_exp_f32_e32 v20, v20
	v_exp_f32_e32 v21, v21
	v_exp_f32_e32 v22, v22
	v_exp_f32_e32 v23, v23
	v_exp_f32_e32 v24, v24
	v_exp_f32_e32 v25, v25
	v_exp_f32_e32 v26, v26
	v_exp_f32_e32 v27, v27
	v_exp_f32_e32 v28, v28
	v_exp_f32_e32 v29, v29
	v_exp_f32_e32 v30, v30
	v_exp_f32_e32 v31, v31
	v_pk_add_f32 v[0:1], v[0:1], 1.0 op_sel_hi:[1,0]
	v_pk_add_f32 v[2:3], v[2:3], 1.0 op_sel_hi:[1,0]
	v_pk_add_f32 v[4:5], v[4:5], 1.0 op_sel_hi:[1,0]
	v_pk_add_f32 v[6:7], v[6:7], 1.0 op_sel_hi:[1,0]
	v_pk_add_f32 v[8:9], v[8:9], 1.0 op_sel_hi:[1,0]
	v_pk_add_f32 v[10:11], v[10:11], 1.0 op_sel_hi:[1,0]
	v_pk_add_f32 v[12:13], v[12:13], 1.0 op_sel_hi:[1,0]
	v_pk_add_f32 v[14:15], v[14:15], 1.0 op_sel_hi:[1,0]
	v_pk_add_f32 v[16:17], v[16:17], 1.0 op_sel_hi:[1,0]
	v_pk_add_f32 v[18:19], v[18:19], 1.0 op_sel_hi:[1,0]
	v_pk_add_f32 v[20:21], v[20:21], 1.0 op_sel_hi:[1,0]
	v_pk_add_f32 v[22:23], v[22:23], 1.0 op_sel_hi:[1,0]
	v_pk_add_f32 v[24:25], v[24:25], 1.0 op_sel_hi:[1,0]
	v_pk_add_f32 v[26:27], v[26:27], 1.0 op_sel_hi:[1,0]
	v_pk_add_f32 v[28:29], v[28:29], 1.0 op_sel_hi:[1,0]
	v_pk_add_f32 v[30:31], v[30:31], 1.0 op_sel_hi:[1,0]
	v_rcp_f32_e32 v0, v0
	v_rcp_f32_e32 v1, v1
	v_rcp_f32_e32 v2, v2
	v_rcp_f32_e32 v3, v3
	v_rcp_f32_e32 v4, v4
	v_rcp_f32_e32 v5, v5
	v_rcp_f32_e32 v6, v6
	v_rcp_f32_e32 v7, v7
	v_rcp_f32_e32 v8, v8
	v_rcp_f32_e32 v9, v9
	v_rcp_f32_e32 v10, v10
	v_rcp_f32_e32 v11, v11
	v_rcp_f32_e32 v12, v12
	v_rcp_f32_e32 v13, v13
	v_rcp_f32_e32 v14, v14
	v_rcp_f32_e32 v15, v15
	v_rcp_f32_e32 v16, v16
	v_rcp_f32_e32 v17, v17
	v_rcp_f32_e32 v18, v18
	v_rcp_f32_e32 v19, v19
	v_rcp_f32_e32 v20, v20
	v_rcp_f32_e32 v21, v21
	v_rcp_f32_e32 v22, v22
	v_rcp_f32_e32 v23, v23
	v_rcp_f32_e32 v24, v24
	v_rcp_f32_e32 v25, v25
	v_rcp_f32_e32 v26, v26
	v_rcp_f32_e32 v27, v27
	v_rcp_f32_e32 v28, v28
	v_rcp_f32_e32 v29, v29
	v_rcp_f32_e32 v30, v30
	v_rcp_f32_e32 v31, v31
	s_nop 0
	v_cvt_pk_bf16_f32 v0, v0, v1
	v_cvt_pk_bf16_f32 v1, v2, v3
	v_cvt_pk_bf16_f32 v2, v4, v5
	v_cvt_pk_bf16_f32 v3, v6, v7
	v_cvt_pk_bf16_f32 v4, v8, v9
	v_cvt_pk_bf16_f32 v5, v10, v11
	v_cvt_pk_bf16_f32 v6, v12, v13
	v_cvt_pk_bf16_f32 v7, v14, v15
	v_cvt_pk_bf16_f32 v16, v16, v17
	v_cvt_pk_bf16_f32 v17, v18, v19
	v_cvt_pk_bf16_f32 v18, v20, v21
	v_cvt_pk_bf16_f32 v19, v22, v23
	v_cvt_pk_bf16_f32 v20, v24, v25
	v_cvt_pk_bf16_f32 v21, v26, v27
	v_cvt_pk_bf16_f32 v22, v28, v29
	v_cvt_pk_bf16_f32 v23, v30, v31
	v_permlane32_swap_b32_e32 v0, v2
	v_permlane32_swap_b32_e32 v1, v3
	v_permlane32_swap_b32_e32 v4, v6
	v_permlane32_swap_b32_e32 v5, v7
	v_permlane32_swap_b32_e32 v16, v18
	v_permlane32_swap_b32_e32 v17, v19
	v_permlane32_swap_b32_e32 v20, v22
	v_permlane32_swap_b32_e32 v21, v23
	global_store_dwordx4 v181, v[0:3], s[74:75] offset:0
	global_store_dwordx4 v181, v[4:7], s[74:75] offset:32
	global_store_dwordx4 v181, v[16:19], s[74:75] offset:64
	global_store_dwordx4 v181, v[20:23], s[74:75] offset:96
	s_add_u32 s74, s74, 0x44000
	s_addc_u32 s75, s75, 0
	v_pk_fma_f32 v[32:33], v[32:33], v[172:173], v[198:199] op_sel:[0,1,0] op_sel_hi:[1,1,1]
	v_pk_fma_f32 v[34:35], v[34:35], v[172:173], v[200:201] op_sel:[0,1,0] op_sel_hi:[1,1,1]
	v_pk_fma_f32 v[36:37], v[36:37], v[172:173], v[202:203] op_sel:[0,1,0] op_sel_hi:[1,1,1]
	v_pk_fma_f32 v[38:39], v[38:39], v[172:173], v[204:205] op_sel:[0,1,0] op_sel_hi:[1,1,1]
	v_pk_fma_f32 v[40:41], v[40:41], v[172:173], v[206:207] op_sel:[0,1,0] op_sel_hi:[1,1,1]
	v_pk_fma_f32 v[42:43], v[42:43], v[172:173], v[208:209] op_sel:[0,1,0] op_sel_hi:[1,1,1]
	v_pk_fma_f32 v[44:45], v[44:45], v[172:173], v[210:211] op_sel:[0,1,0] op_sel_hi:[1,1,1]
	v_pk_fma_f32 v[46:47], v[46:47], v[172:173], v[212:213] op_sel:[0,1,0] op_sel_hi:[1,1,1]
	v_pk_fma_f32 v[48:49], v[48:49], v[172:173], v[214:215] op_sel:[0,1,0] op_sel_hi:[1,1,1]
	v_pk_fma_f32 v[50:51], v[50:51], v[172:173], v[216:217] op_sel:[0,1,0] op_sel_hi:[1,1,1]
	v_pk_fma_f32 v[52:53], v[52:53], v[172:173], v[218:219] op_sel:[0,1,0] op_sel_hi:[1,1,1]
	v_pk_fma_f32 v[54:55], v[54:55], v[172:173], v[220:221] op_sel:[0,1,0] op_sel_hi:[1,1,1]
	v_pk_fma_f32 v[56:57], v[56:57], v[172:173], v[222:223] op_sel:[0,1,0] op_sel_hi:[1,1,1]
	v_pk_fma_f32 v[58:59], v[58:59], v[172:173], v[224:225] op_sel:[0,1,0] op_sel_hi:[1,1,1]
	v_pk_fma_f32 v[60:61], v[60:61], v[172:173], v[226:227] op_sel:[0,1,0] op_sel_hi:[1,1,1]
	v_pk_fma_f32 v[62:63], v[62:63], v[172:173], v[228:229] op_sel:[0,1,0] op_sel_hi:[1,1,1]
	v_exp_f32_e32 v32, v32
	v_exp_f32_e32 v33, v33
	v_exp_f32_e32 v34, v34
	v_exp_f32_e32 v35, v35
	v_exp_f32_e32 v36, v36
	v_exp_f32_e32 v37, v37
	v_exp_f32_e32 v38, v38
	v_exp_f32_e32 v39, v39
	v_exp_f32_e32 v40, v40
	v_exp_f32_e32 v41, v41
	v_exp_f32_e32 v42, v42
	v_exp_f32_e32 v43, v43
	v_exp_f32_e32 v44, v44
	v_exp_f32_e32 v45, v45
	v_exp_f32_e32 v46, v46
	v_exp_f32_e32 v47, v47
	v_exp_f32_e32 v48, v48
	v_exp_f32_e32 v49, v49
	v_exp_f32_e32 v50, v50
	v_exp_f32_e32 v51, v51
	v_exp_f32_e32 v52, v52
	v_exp_f32_e32 v53, v53
	v_exp_f32_e32 v54, v54
	v_exp_f32_e32 v55, v55
	v_exp_f32_e32 v56, v56
	v_exp_f32_e32 v57, v57
	v_exp_f32_e32 v58, v58
	v_exp_f32_e32 v59, v59
	v_exp_f32_e32 v60, v60
	v_exp_f32_e32 v61, v61
	v_exp_f32_e32 v62, v62
	v_exp_f32_e32 v63, v63
	v_pk_add_f32 v[32:33], v[32:33], 1.0 op_sel_hi:[1,0]
	v_pk_add_f32 v[34:35], v[34:35], 1.0 op_sel_hi:[1,0]
	v_pk_add_f32 v[36:37], v[36:37], 1.0 op_sel_hi:[1,0]
	v_pk_add_f32 v[38:39], v[38:39], 1.0 op_sel_hi:[1,0]
	v_pk_add_f32 v[40:41], v[40:41], 1.0 op_sel_hi:[1,0]
	v_pk_add_f32 v[42:43], v[42:43], 1.0 op_sel_hi:[1,0]
	v_pk_add_f32 v[44:45], v[44:45], 1.0 op_sel_hi:[1,0]
	v_pk_add_f32 v[46:47], v[46:47], 1.0 op_sel_hi:[1,0]
	v_pk_add_f32 v[48:49], v[48:49], 1.0 op_sel_hi:[1,0]
	v_pk_add_f32 v[50:51], v[50:51], 1.0 op_sel_hi:[1,0]
	v_pk_add_f32 v[52:53], v[52:53], 1.0 op_sel_hi:[1,0]
	v_pk_add_f32 v[54:55], v[54:55], 1.0 op_sel_hi:[1,0]
	v_pk_add_f32 v[56:57], v[56:57], 1.0 op_sel_hi:[1,0]
	v_pk_add_f32 v[58:59], v[58:59], 1.0 op_sel_hi:[1,0]
	v_pk_add_f32 v[60:61], v[60:61], 1.0 op_sel_hi:[1,0]
	v_pk_add_f32 v[62:63], v[62:63], 1.0 op_sel_hi:[1,0]
	v_rcp_f32_e32 v32, v32
	v_rcp_f32_e32 v33, v33
	v_rcp_f32_e32 v34, v34
	v_rcp_f32_e32 v35, v35
	v_rcp_f32_e32 v36, v36
	v_rcp_f32_e32 v37, v37
	v_rcp_f32_e32 v38, v38
	v_rcp_f32_e32 v39, v39
	v_rcp_f32_e32 v40, v40
	v_rcp_f32_e32 v41, v41
	v_rcp_f32_e32 v42, v42
	v_rcp_f32_e32 v43, v43
	v_rcp_f32_e32 v44, v44
	v_rcp_f32_e32 v45, v45
	v_rcp_f32_e32 v46, v46
	v_rcp_f32_e32 v47, v47
	v_rcp_f32_e32 v48, v48
	v_rcp_f32_e32 v49, v49
	v_rcp_f32_e32 v50, v50
	v_rcp_f32_e32 v51, v51
	v_rcp_f32_e32 v52, v52
	v_rcp_f32_e32 v53, v53
	v_rcp_f32_e32 v54, v54
	v_rcp_f32_e32 v55, v55
	v_rcp_f32_e32 v56, v56
	v_rcp_f32_e32 v57, v57
	v_rcp_f32_e32 v58, v58
	v_rcp_f32_e32 v59, v59
	v_rcp_f32_e32 v60, v60
	v_rcp_f32_e32 v61, v61
	v_rcp_f32_e32 v62, v62
	v_rcp_f32_e32 v63, v63
	s_nop 0
	v_cvt_pk_bf16_f32 v32, v32, v33
	v_cvt_pk_bf16_f32 v33, v34, v35
	v_cvt_pk_bf16_f32 v34, v36, v37
	v_cvt_pk_bf16_f32 v35, v38, v39
	v_cvt_pk_bf16_f32 v36, v40, v41
	v_cvt_pk_bf16_f32 v37, v42, v43
	v_cvt_pk_bf16_f32 v38, v44, v45
	v_cvt_pk_bf16_f32 v39, v46, v47
	v_cvt_pk_bf16_f32 v48, v48, v49
	v_cvt_pk_bf16_f32 v49, v50, v51
	v_cvt_pk_bf16_f32 v50, v52, v53
	v_cvt_pk_bf16_f32 v51, v54, v55
	v_cvt_pk_bf16_f32 v52, v56, v57
	v_cvt_pk_bf16_f32 v53, v58, v59
	v_cvt_pk_bf16_f32 v54, v60, v61
	v_cvt_pk_bf16_f32 v55, v62, v63
	v_permlane32_swap_b32_e32 v32, v34
	v_permlane32_swap_b32_e32 v33, v35
	v_permlane32_swap_b32_e32 v36, v38
	v_permlane32_swap_b32_e32 v37, v39
	v_permlane32_swap_b32_e32 v48, v50
	v_permlane32_swap_b32_e32 v49, v51
	v_permlane32_swap_b32_e32 v52, v54
	v_permlane32_swap_b32_e32 v53, v55
	global_store_dwordx4 v181, v[32:35], s[74:75] offset:0
	global_store_dwordx4 v181, v[36:39], s[74:75] offset:32
	global_store_dwordx4 v181, v[48:51], s[74:75] offset:64
	global_store_dwordx4 v181, v[52:55], s[74:75] offset:96
	s_add_u32 s74, s74, 0x44000
	s_addc_u32 s75, s75, 0
	v_pk_fma_f32 v[64:65], v[64:65], v[174:175], v[198:199] op_sel_hi:[1,0,1]
	v_pk_fma_f32 v[66:67], v[66:67], v[174:175], v[200:201] op_sel_hi:[1,0,1]
	v_pk_fma_f32 v[68:69], v[68:69], v[174:175], v[202:203] op_sel_hi:[1,0,1]
	v_pk_fma_f32 v[70:71], v[70:71], v[174:175], v[204:205] op_sel_hi:[1,0,1]
	v_pk_fma_f32 v[72:73], v[72:73], v[174:175], v[206:207] op_sel_hi:[1,0,1]
	v_pk_fma_f32 v[74:75], v[74:75], v[174:175], v[208:209] op_sel_hi:[1,0,1]
	v_pk_fma_f32 v[76:77], v[76:77], v[174:175], v[210:211] op_sel_hi:[1,0,1]
	v_pk_fma_f32 v[78:79], v[78:79], v[174:175], v[212:213] op_sel_hi:[1,0,1]
	v_pk_fma_f32 v[80:81], v[80:81], v[174:175], v[214:215] op_sel_hi:[1,0,1]
	v_pk_fma_f32 v[82:83], v[82:83], v[174:175], v[216:217] op_sel_hi:[1,0,1]
	v_pk_fma_f32 v[84:85], v[84:85], v[174:175], v[218:219] op_sel_hi:[1,0,1]
	v_pk_fma_f32 v[86:87], v[86:87], v[174:175], v[220:221] op_sel_hi:[1,0,1]
	v_pk_fma_f32 v[88:89], v[88:89], v[174:175], v[222:223] op_sel_hi:[1,0,1]
	v_pk_fma_f32 v[90:91], v[90:91], v[174:175], v[224:225] op_sel_hi:[1,0,1]
	v_pk_fma_f32 v[92:93], v[92:93], v[174:175], v[226:227] op_sel_hi:[1,0,1]
	v_pk_fma_f32 v[94:95], v[94:95], v[174:175], v[228:229] op_sel_hi:[1,0,1]
	v_exp_f32_e32 v64, v64
	v_exp_f32_e32 v65, v65
	v_exp_f32_e32 v66, v66
	v_exp_f32_e32 v67, v67
	v_exp_f32_e32 v68, v68
	v_exp_f32_e32 v69, v69
	v_exp_f32_e32 v70, v70
	v_exp_f32_e32 v71, v71
	v_exp_f32_e32 v72, v72
	v_exp_f32_e32 v73, v73
	v_exp_f32_e32 v74, v74
	v_exp_f32_e32 v75, v75
	v_exp_f32_e32 v76, v76
	v_exp_f32_e32 v77, v77
	v_exp_f32_e32 v78, v78
	v_exp_f32_e32 v79, v79
	v_exp_f32_e32 v80, v80
	v_exp_f32_e32 v81, v81
	v_exp_f32_e32 v82, v82
	v_exp_f32_e32 v83, v83
	v_exp_f32_e32 v84, v84
	v_exp_f32_e32 v85, v85
	v_exp_f32_e32 v86, v86
	v_exp_f32_e32 v87, v87
	v_exp_f32_e32 v88, v88
	v_exp_f32_e32 v89, v89
	v_exp_f32_e32 v90, v90
	v_exp_f32_e32 v91, v91
	v_exp_f32_e32 v92, v92
	v_exp_f32_e32 v93, v93
	v_exp_f32_e32 v94, v94
	v_exp_f32_e32 v95, v95
	v_pk_add_f32 v[64:65], v[64:65], 1.0 op_sel_hi:[1,0]
	v_pk_add_f32 v[66:67], v[66:67], 1.0 op_sel_hi:[1,0]
	v_pk_add_f32 v[68:69], v[68:69], 1.0 op_sel_hi:[1,0]
	v_pk_add_f32 v[70:71], v[70:71], 1.0 op_sel_hi:[1,0]
	v_pk_add_f32 v[72:73], v[72:73], 1.0 op_sel_hi:[1,0]
	v_pk_add_f32 v[74:75], v[74:75], 1.0 op_sel_hi:[1,0]
	v_pk_add_f32 v[76:77], v[76:77], 1.0 op_sel_hi:[1,0]
	v_pk_add_f32 v[78:79], v[78:79], 1.0 op_sel_hi:[1,0]
	v_pk_add_f32 v[80:81], v[80:81], 1.0 op_sel_hi:[1,0]
	v_pk_add_f32 v[82:83], v[82:83], 1.0 op_sel_hi:[1,0]
	v_pk_add_f32 v[84:85], v[84:85], 1.0 op_sel_hi:[1,0]
	v_pk_add_f32 v[86:87], v[86:87], 1.0 op_sel_hi:[1,0]
	v_pk_add_f32 v[88:89], v[88:89], 1.0 op_sel_hi:[1,0]
	v_pk_add_f32 v[90:91], v[90:91], 1.0 op_sel_hi:[1,0]
	v_pk_add_f32 v[92:93], v[92:93], 1.0 op_sel_hi:[1,0]
	v_pk_add_f32 v[94:95], v[94:95], 1.0 op_sel_hi:[1,0]
	v_rcp_f32_e32 v64, v64
	v_rcp_f32_e32 v65, v65
	v_rcp_f32_e32 v66, v66
	v_rcp_f32_e32 v67, v67
	v_rcp_f32_e32 v68, v68
	v_rcp_f32_e32 v69, v69
	v_rcp_f32_e32 v70, v70
	v_rcp_f32_e32 v71, v71
	v_rcp_f32_e32 v72, v72
	v_rcp_f32_e32 v73, v73
	v_rcp_f32_e32 v74, v74
	v_rcp_f32_e32 v75, v75
	v_rcp_f32_e32 v76, v76
	v_rcp_f32_e32 v77, v77
	v_rcp_f32_e32 v78, v78
	v_rcp_f32_e32 v79, v79
	v_rcp_f32_e32 v80, v80
	v_rcp_f32_e32 v81, v81
	v_rcp_f32_e32 v82, v82
	v_rcp_f32_e32 v83, v83
	v_rcp_f32_e32 v84, v84
	v_rcp_f32_e32 v85, v85
	v_rcp_f32_e32 v86, v86
	v_rcp_f32_e32 v87, v87
	v_rcp_f32_e32 v88, v88
	v_rcp_f32_e32 v89, v89
	v_rcp_f32_e32 v90, v90
	v_rcp_f32_e32 v91, v91
	v_rcp_f32_e32 v92, v92
	v_rcp_f32_e32 v93, v93
	v_rcp_f32_e32 v94, v94
	v_rcp_f32_e32 v95, v95
	s_nop 0
	v_cvt_pk_bf16_f32 v64, v64, v65
	v_cvt_pk_bf16_f32 v65, v66, v67
	v_cvt_pk_bf16_f32 v66, v68, v69
	v_cvt_pk_bf16_f32 v67, v70, v71
	v_cvt_pk_bf16_f32 v68, v72, v73
	v_cvt_pk_bf16_f32 v69, v74, v75
	v_cvt_pk_bf16_f32 v70, v76, v77
	v_cvt_pk_bf16_f32 v71, v78, v79
	v_cvt_pk_bf16_f32 v80, v80, v81
	v_cvt_pk_bf16_f32 v81, v82, v83
	v_cvt_pk_bf16_f32 v82, v84, v85
	v_cvt_pk_bf16_f32 v83, v86, v87
	v_cvt_pk_bf16_f32 v84, v88, v89
	v_cvt_pk_bf16_f32 v85, v90, v91
	v_cvt_pk_bf16_f32 v86, v92, v93
	v_cvt_pk_bf16_f32 v87, v94, v95
	v_permlane32_swap_b32_e32 v64, v66
	v_permlane32_swap_b32_e32 v65, v67
	v_permlane32_swap_b32_e32 v68, v70
	v_permlane32_swap_b32_e32 v69, v71
	v_permlane32_swap_b32_e32 v80, v82
	v_permlane32_swap_b32_e32 v81, v83
	v_permlane32_swap_b32_e32 v84, v86
	v_permlane32_swap_b32_e32 v85, v87
	global_store_dwordx4 v181, v[64:67], s[74:75] offset:0
	global_store_dwordx4 v181, v[68:71], s[74:75] offset:32
	global_store_dwordx4 v181, v[80:83], s[74:75] offset:64
	global_store_dwordx4 v181, v[84:87], s[74:75] offset:96
	s_add_u32 s74, s74, 0x44000
	s_addc_u32 s75, s75, 0
	v_pk_fma_f32 v[96:97], v[96:97], v[174:175], v[198:199] op_sel:[0,1,0] op_sel_hi:[1,1,1]
	v_pk_fma_f32 v[98:99], v[98:99], v[174:175], v[200:201] op_sel:[0,1,0] op_sel_hi:[1,1,1]
	v_pk_fma_f32 v[100:101], v[100:101], v[174:175], v[202:203] op_sel:[0,1,0] op_sel_hi:[1,1,1]
	v_pk_fma_f32 v[102:103], v[102:103], v[174:175], v[204:205] op_sel:[0,1,0] op_sel_hi:[1,1,1]
	v_pk_fma_f32 v[104:105], v[104:105], v[174:175], v[206:207] op_sel:[0,1,0] op_sel_hi:[1,1,1]
	v_pk_fma_f32 v[106:107], v[106:107], v[174:175], v[208:209] op_sel:[0,1,0] op_sel_hi:[1,1,1]
	v_pk_fma_f32 v[108:109], v[108:109], v[174:175], v[210:211] op_sel:[0,1,0] op_sel_hi:[1,1,1]
	v_pk_fma_f32 v[110:111], v[110:111], v[174:175], v[212:213] op_sel:[0,1,0] op_sel_hi:[1,1,1]
	v_pk_fma_f32 v[112:113], v[112:113], v[174:175], v[214:215] op_sel:[0,1,0] op_sel_hi:[1,1,1]
	v_pk_fma_f32 v[114:115], v[114:115], v[174:175], v[216:217] op_sel:[0,1,0] op_sel_hi:[1,1,1]
	v_pk_fma_f32 v[116:117], v[116:117], v[174:175], v[218:219] op_sel:[0,1,0] op_sel_hi:[1,1,1]
	v_pk_fma_f32 v[118:119], v[118:119], v[174:175], v[220:221] op_sel:[0,1,0] op_sel_hi:[1,1,1]
	v_pk_fma_f32 v[120:121], v[120:121], v[174:175], v[222:223] op_sel:[0,1,0] op_sel_hi:[1,1,1]
	v_pk_fma_f32 v[122:123], v[122:123], v[174:175], v[224:225] op_sel:[0,1,0] op_sel_hi:[1,1,1]
	v_pk_fma_f32 v[124:125], v[124:125], v[174:175], v[226:227] op_sel:[0,1,0] op_sel_hi:[1,1,1]
	v_pk_fma_f32 v[126:127], v[126:127], v[174:175], v[228:229] op_sel:[0,1,0] op_sel_hi:[1,1,1]
	v_exp_f32_e32 v96, v96
	v_exp_f32_e32 v97, v97
	v_exp_f32_e32 v98, v98
	v_exp_f32_e32 v99, v99
	v_exp_f32_e32 v100, v100
	v_exp_f32_e32 v101, v101
	v_exp_f32_e32 v102, v102
	v_exp_f32_e32 v103, v103
	v_exp_f32_e32 v104, v104
	v_exp_f32_e32 v105, v105
	v_exp_f32_e32 v106, v106
	v_exp_f32_e32 v107, v107
	v_exp_f32_e32 v108, v108
	v_exp_f32_e32 v109, v109
	v_exp_f32_e32 v110, v110
	v_exp_f32_e32 v111, v111
	v_exp_f32_e32 v112, v112
	v_exp_f32_e32 v113, v113
	v_exp_f32_e32 v114, v114
	v_exp_f32_e32 v115, v115
	v_exp_f32_e32 v116, v116
	v_exp_f32_e32 v117, v117
	v_exp_f32_e32 v118, v118
	v_exp_f32_e32 v119, v119
	v_exp_f32_e32 v120, v120
	v_exp_f32_e32 v121, v121
	v_exp_f32_e32 v122, v122
	v_exp_f32_e32 v123, v123
	v_exp_f32_e32 v124, v124
	v_exp_f32_e32 v125, v125
	v_exp_f32_e32 v126, v126
	v_exp_f32_e32 v127, v127
	v_pk_add_f32 v[96:97], v[96:97], 1.0 op_sel_hi:[1,0]
	v_pk_add_f32 v[98:99], v[98:99], 1.0 op_sel_hi:[1,0]
	v_pk_add_f32 v[100:101], v[100:101], 1.0 op_sel_hi:[1,0]
	v_pk_add_f32 v[102:103], v[102:103], 1.0 op_sel_hi:[1,0]
	v_pk_add_f32 v[104:105], v[104:105], 1.0 op_sel_hi:[1,0]
	v_pk_add_f32 v[106:107], v[106:107], 1.0 op_sel_hi:[1,0]
	v_pk_add_f32 v[108:109], v[108:109], 1.0 op_sel_hi:[1,0]
	v_pk_add_f32 v[110:111], v[110:111], 1.0 op_sel_hi:[1,0]
	v_pk_add_f32 v[112:113], v[112:113], 1.0 op_sel_hi:[1,0]
	v_pk_add_f32 v[114:115], v[114:115], 1.0 op_sel_hi:[1,0]
	v_pk_add_f32 v[116:117], v[116:117], 1.0 op_sel_hi:[1,0]
	v_pk_add_f32 v[118:119], v[118:119], 1.0 op_sel_hi:[1,0]
	v_pk_add_f32 v[120:121], v[120:121], 1.0 op_sel_hi:[1,0]
	v_pk_add_f32 v[122:123], v[122:123], 1.0 op_sel_hi:[1,0]
	v_pk_add_f32 v[124:125], v[124:125], 1.0 op_sel_hi:[1,0]
	v_pk_add_f32 v[126:127], v[126:127], 1.0 op_sel_hi:[1,0]
	v_rcp_f32_e32 v96, v96
	v_rcp_f32_e32 v97, v97
	v_rcp_f32_e32 v98, v98
	v_rcp_f32_e32 v99, v99
	v_rcp_f32_e32 v100, v100
	v_rcp_f32_e32 v101, v101
	v_rcp_f32_e32 v102, v102
	v_rcp_f32_e32 v103, v103
	v_rcp_f32_e32 v104, v104
	v_rcp_f32_e32 v105, v105
	v_rcp_f32_e32 v106, v106
	v_rcp_f32_e32 v107, v107
	v_rcp_f32_e32 v108, v108
	v_rcp_f32_e32 v109, v109
	v_rcp_f32_e32 v110, v110
	v_rcp_f32_e32 v111, v111
	v_rcp_f32_e32 v112, v112
	v_rcp_f32_e32 v113, v113
	v_rcp_f32_e32 v114, v114
	v_rcp_f32_e32 v115, v115
	v_rcp_f32_e32 v116, v116
	v_rcp_f32_e32 v117, v117
	v_rcp_f32_e32 v118, v118
	v_rcp_f32_e32 v119, v119
	v_rcp_f32_e32 v120, v120
	v_rcp_f32_e32 v121, v121
	v_rcp_f32_e32 v122, v122
	v_rcp_f32_e32 v123, v123
	v_rcp_f32_e32 v124, v124
	v_rcp_f32_e32 v125, v125
	v_rcp_f32_e32 v126, v126
	v_rcp_f32_e32 v127, v127
	s_nop 0
	v_cvt_pk_bf16_f32 v96, v96, v97
	v_cvt_pk_bf16_f32 v97, v98, v99
	v_cvt_pk_bf16_f32 v98, v100, v101
	v_cvt_pk_bf16_f32 v99, v102, v103
	v_cvt_pk_bf16_f32 v100, v104, v105
	v_cvt_pk_bf16_f32 v101, v106, v107
	v_cvt_pk_bf16_f32 v102, v108, v109
	v_cvt_pk_bf16_f32 v103, v110, v111
	v_cvt_pk_bf16_f32 v112, v112, v113
	v_cvt_pk_bf16_f32 v113, v114, v115
	v_cvt_pk_bf16_f32 v114, v116, v117
	v_cvt_pk_bf16_f32 v115, v118, v119
	v_cvt_pk_bf16_f32 v116, v120, v121
	v_cvt_pk_bf16_f32 v117, v122, v123
	v_cvt_pk_bf16_f32 v118, v124, v125
	v_cvt_pk_bf16_f32 v119, v126, v127
	v_permlane32_swap_b32_e32 v96, v98
	v_permlane32_swap_b32_e32 v97, v99
	v_permlane32_swap_b32_e32 v100, v102
	v_permlane32_swap_b32_e32 v101, v103
	v_permlane32_swap_b32_e32 v112, v114
	v_permlane32_swap_b32_e32 v113, v115
	v_permlane32_swap_b32_e32 v116, v118
	v_permlane32_swap_b32_e32 v117, v119
	global_store_dwordx4 v181, v[96:99], s[74:75] offset:0
	global_store_dwordx4 v181, v[100:103], s[74:75] offset:32
	global_store_dwordx4 v181, v[112:115], s[74:75] offset:64
	global_store_dwordx4 v181, v[116:119], s[74:75] offset:96
	s_branch .Lpe_ret_L0
.Lpe_vt_L0:
	s_lshl_b32 s35, s34, 2
	s_add_u32 s35, s35, s28
	s_add_u32 s36, s28, 6
	s_cmp_eq_u32 s25, 8
	s_cselect_b32 s35, s36, s35
	s_lshr_b32 s36, s29, 11
	s_mul_i32 s36, s36, 10
	s_add_u32 s36, s36, s35
	s_lshl_b32 s36, s36, 18
	s_and_b32 s37, s29, 0x7ff
	s_lshl_b32 s37, s37, 1
	s_add_u32 s36, s36, s37
	s_add_u32 s38, s72, 0x14920000
	s_addc_u32 s39, s73, 0
	s_add_u32 s38, s38, s36
	s_addc_u32 s39, s39, 0
	s_mul_i32 s36, s26, 10240
	s_add_u32 s36, s36, 0x10000
	v_lshlrev_b32_e32 v180, 1, v197
	v_mul_u32_u24_e32 v181, 36, v146
	v_add3_u32 v180, v180, v181, s36
	v_lshrrev_b32_e32 v181, 3, v179
	v_and_b32_e32 v146, 7, v179
	v_lshlrev_b32_e32 v146, 4, v146
	v_mul_u32_u24_e32 v198, 144, v181
	v_add3_u32 v198, v198, v146, s36
	v_lshl_add_u32 v199, v181, 12, v146
	s_waitcnt vmcnt(0)
	v_mov_b32_e32 v197, 0x358637bd
	v_pk_add_f32 v[128:129], v[128:129], v[130:131]
	v_pk_add_f32 v[132:133], v[132:133], v[134:135]
	v_pk_add_f32 v[136:137], v[136:137], v[138:139]
	v_pk_add_f32 v[140:141], v[140:141], v[142:143]
	v_pk_add_f32 v[164:165], v[164:165], v[166:167]
	v_pk_add_f32 v[168:169], v[168:169], v[170:171]
	v_pk_add_f32 v[246:247], v[246:247], v[248:249]
	v_pk_add_f32 v[250:251], v[250:251], v[252:253]
	v_pk_add_f32 v[128:129], v[128:129], v[132:133]
	v_pk_add_f32 v[136:137], v[136:137], v[140:141]
	v_pk_add_f32 v[164:165], v[164:165], v[168:169]
	v_pk_add_f32 v[246:247], v[246:247], v[250:251]
	v_add_f32_e32 v128, v128, v129
	v_add_f32_e32 v136, v136, v137
	v_add_f32_e32 v164, v164, v165
	v_add_f32_e32 v246, v246, v247
	v_fmamk_f32 v128, v128, 0x3a800000, v197
	v_fmamk_f32 v136, v136, 0x3a800000, v197
	v_fmamk_f32 v164, v164, 0x3a800000, v197
	v_fmamk_f32 v246, v246, 0x3a800000, v197
	v_rsq_f32_e32 v172, v128
	v_rsq_f32_e32 v173, v136
	v_rsq_f32_e32 v174, v164
	v_rsq_f32_e32 v175, v246
	s_nop 0
	s_add_u32 s76, s99, s90
	s_cmp_lt_u32 s76, 0x440
	s_cselect_b32 s80, 1, 0
	s_cselect_b32 s83, 0x200000, 0
	s_lshl_b32 s76, s24, 19
	s_lshl_b32 s77, s26, 16
	s_add_u32 s76, s76, s77
	s_and_b32 s77, s24, 7
	s_lshl_b32 s77, s77, 8
	s_add_u32 s76, s76, s77
	s_add_u32 s78, s72, 0xa120000
	s_addc_u32 s79, s73, 0
	s_add_u32 s78, s78, s76
	s_addc_u32 s79, s79, 0
	s_lshl_b32 s76, s25, 19
	s_add_u32 s76, s76, s83
	s_add_u32 s76, s76, s77
	s_lshl_b32 s77, s26, 16
	s_add_u32 s76, s76, s77
	s_add_u32 s82, s72, 0x0
	s_addc_u32 s83, s73, 0
	s_add_u32 s82, s82, s76
	s_addc_u32 s83, s83, 0
	s_lshl_b32 s76, s26, 12
	s_add_u32 s76, s76, s56
	s_mov_b32 m0, s76
	s_nop 0
	global_load_lds_dwordx4 v145, s[78:79]
	s_add_u32 s78, s78, 0x4000
	s_addc_u32 s79, s79, 0
	s_add_u32 s76, s76, 0x400
	s_mov_b32 m0, s76
	s_nop 0
	global_load_lds_dwordx4 v185, s[78:79]
	s_add_u32 s78, s78, 0x4000
	s_addc_u32 s79, s79, 0
	s_add_u32 s76, s76, 0x400
	s_mov_b32 m0, s76
	s_nop 0
	global_load_lds_dwordx4 v145, s[78:79]
	s_add_u32 s78, s78, 0x4000
	s_addc_u32 s79, s79, 0
	s_add_u32 s76, s76, 0x400
	s_mov_b32 m0, s76
	s_nop 0
	global_load_lds_dwordx4 v185, s[78:79]
	s_add_u32 s78, s78, 0x4000
	s_addc_u32 s79, s79, 0
	s_add_u32 s76, s76, 0x400
	s_sub_u32 s76, s76, s56
	s_add_u32 s76, s76, 0x7000
	s_mov_b32 m0, s76
	s_nop 0
	global_load_lds_dwordx4 v145, s[82:83]
	s_add_u32 s82, s82, 0x4000
	s_addc_u32 s83, s83, 0
	s_add_u32 s76, s76, 0x400
	s_mov_b32 m0, s76
	s_nop 0
	global_load_lds_dwordx4 v185, s[82:83]
	s_add_u32 s82, s82, 0x4000
	s_addc_u32 s83, s83, 0
	s_add_u32 s76, s76, 0x400
	s_mov_b32 m0, s76
	s_nop 0
	global_load_lds_dwordx4 v145, s[82:83]
	s_add_u32 s82, s82, 0x4000
	s_addc_u32 s83, s83, 0
	s_add_u32 s76, s76, 0x400
	s_mov_b32 m0, s76
	s_nop 0
	global_load_lds_dwordx4 v185, s[82:83]
	s_add_u32 s82, s82, 0x4000
	s_addc_u32 s83, s83, 0
	s_add_u32 s76, s76, 0x400
	v_pk_mul_f32 v[0:1], v[0:1], v[172:173] op_sel_hi:[1,0]
	v_pk_mul_f32 v[2:3], v[2:3], v[172:173] op_sel_hi:[1,0]
	v_pk_mul_f32 v[4:5], v[4:5], v[172:173] op_sel_hi:[1,0]
	v_pk_mul_f32 v[6:7], v[6:7], v[172:173] op_sel_hi:[1,0]
	v_pk_mul_f32 v[8:9], v[8:9], v[172:173] op_sel_hi:[1,0]
	v_pk_mul_f32 v[10:11], v[10:11], v[172:173] op_sel_hi:[1,0]
	v_pk_mul_f32 v[12:13], v[12:13], v[172:173] op_sel_hi:[1,0]
	v_pk_mul_f32 v[14:15], v[14:15], v[172:173] op_sel_hi:[1,0]
	v_pk_mul_f32 v[16:17], v[16:17], v[172:173] op_sel_hi:[1,0]
	v_pk_mul_f32 v[18:19], v[18:19], v[172:173] op_sel_hi:[1,0]
	v_pk_mul_f32 v[20:21], v[20:21], v[172:173] op_sel_hi:[1,0]
	v_pk_mul_f32 v[22:23], v[22:23], v[172:173] op_sel_hi:[1,0]
	v_pk_mul_f32 v[24:25], v[24:25], v[172:173] op_sel_hi:[1,0]
	v_pk_mul_f32 v[26:27], v[26:27], v[172:173] op_sel_hi:[1,0]
	v_pk_mul_f32 v[28:29], v[28:29], v[172:173] op_sel_hi:[1,0]
	v_pk_mul_f32 v[30:31], v[30:31], v[172:173] op_sel_hi:[1,0]
	v_pk_mul_f32 v[32:33], v[32:33], v[172:173] op_sel:[0,1] op_sel_hi:[1,1]
	v_pk_mul_f32 v[34:35], v[34:35], v[172:173] op_sel:[0,1] op_sel_hi:[1,1]
	v_pk_mul_f32 v[36:37], v[36:37], v[172:173] op_sel:[0,1] op_sel_hi:[1,1]
	v_pk_mul_f32 v[38:39], v[38:39], v[172:173] op_sel:[0,1] op_sel_hi:[1,1]
	v_pk_mul_f32 v[40:41], v[40:41], v[172:173] op_sel:[0,1] op_sel_hi:[1,1]
	v_pk_mul_f32 v[42:43], v[42:43], v[172:173] op_sel:[0,1] op_sel_hi:[1,1]
	v_pk_mul_f32 v[44:45], v[44:45], v[172:173] op_sel:[0,1] op_sel_hi:[1,1]
	v_pk_mul_f32 v[46:47], v[46:47], v[172:173] op_sel:[0,1] op_sel_hi:[1,1]
	v_pk_mul_f32 v[48:49], v[48:49], v[172:173] op_sel:[0,1] op_sel_hi:[1,1]
	v_pk_mul_f32 v[50:51], v[50:51], v[172:173] op_sel:[0,1] op_sel_hi:[1,1]
	v_pk_mul_f32 v[52:53], v[52:53], v[172:173] op_sel:[0,1] op_sel_hi:[1,1]
	v_pk_mul_f32 v[54:55], v[54:55], v[172:173] op_sel:[0,1] op_sel_hi:[1,1]
	v_pk_mul_f32 v[56:57], v[56:57], v[172:173] op_sel:[0,1] op_sel_hi:[1,1]
	v_pk_mul_f32 v[58:59], v[58:59], v[172:173] op_sel:[0,1] op_sel_hi:[1,1]
	v_pk_mul_f32 v[60:61], v[60:61], v[172:173] op_sel:[0,1] op_sel_hi:[1,1]
	v_pk_mul_f32 v[62:63], v[62:63], v[172:173] op_sel:[0,1] op_sel_hi:[1,1]
	v_pk_mul_f32 v[64:65], v[64:65], v[174:175] op_sel_hi:[1,0]
	v_pk_mul_f32 v[66:67], v[66:67], v[174:175] op_sel_hi:[1,0]
	v_pk_mul_f32 v[68:69], v[68:69], v[174:175] op_sel_hi:[1,0]
	v_pk_mul_f32 v[70:71], v[70:71], v[174:175] op_sel_hi:[1,0]
	v_pk_mul_f32 v[72:73], v[72:73], v[174:175] op_sel_hi:[1,0]
	v_pk_mul_f32 v[74:75], v[74:75], v[174:175] op_sel_hi:[1,0]
	v_pk_mul_f32 v[76:77], v[76:77], v[174:175] op_sel_hi:[1,0]
	v_pk_mul_f32 v[78:79], v[78:79], v[174:175] op_sel_hi:[1,0]
	v_pk_mul_f32 v[80:81], v[80:81], v[174:175] op_sel_hi:[1,0]
	v_pk_mul_f32 v[82:83], v[82:83], v[174:175] op_sel_hi:[1,0]
	v_pk_mul_f32 v[84:85], v[84:85], v[174:175] op_sel_hi:[1,0]
	v_pk_mul_f32 v[86:87], v[86:87], v[174:175] op_sel_hi:[1,0]
	v_pk_mul_f32 v[88:89], v[88:89], v[174:175] op_sel_hi:[1,0]
	v_pk_mul_f32 v[90:91], v[90:91], v[174:175] op_sel_hi:[1,0]
	v_pk_mul_f32 v[92:93], v[92:93], v[174:175] op_sel_hi:[1,0]
	v_pk_mul_f32 v[94:95], v[94:95], v[174:175] op_sel_hi:[1,0]
	v_pk_mul_f32 v[96:97], v[96:97], v[174:175] op_sel:[0,1] op_sel_hi:[1,1]
	v_pk_mul_f32 v[98:99], v[98:99], v[174:175] op_sel:[0,1] op_sel_hi:[1,1]
	v_pk_mul_f32 v[100:101], v[100:101], v[174:175] op_sel:[0,1] op_sel_hi:[1,1]
	v_pk_mul_f32 v[102:103], v[102:103], v[174:175] op_sel:[0,1] op_sel_hi:[1,1]
	v_pk_mul_f32 v[104:105], v[104:105], v[174:175] op_sel:[0,1] op_sel_hi:[1,1]
	v_pk_mul_f32 v[106:107], v[106:107], v[174:175] op_sel:[0,1] op_sel_hi:[1,1]
	v_pk_mul_f32 v[108:109], v[108:109], v[174:175] op_sel:[0,1] op_sel_hi:[1,1]
	v_pk_mul_f32 v[110:111], v[110:111], v[174:175] op_sel:[0,1] op_sel_hi:[1,1]
	v_pk_mul_f32 v[112:113], v[112:113], v[174:175] op_sel:[0,1] op_sel_hi:[1,1]
	v_pk_mul_f32 v[114:115], v[114:115], v[174:175] op_sel:[0,1] op_sel_hi:[1,1]
	v_pk_mul_f32 v[116:117], v[116:117], v[174:175] op_sel:[0,1] op_sel_hi:[1,1]
	v_pk_mul_f32 v[118:119], v[118:119], v[174:175] op_sel:[0,1] op_sel_hi:[1,1]
	v_pk_mul_f32 v[120:121], v[120:121], v[174:175] op_sel:[0,1] op_sel_hi:[1,1]
	v_pk_mul_f32 v[122:123], v[122:123], v[174:175] op_sel:[0,1] op_sel_hi:[1,1]
	v_pk_mul_f32 v[124:125], v[124:125], v[174:175] op_sel:[0,1] op_sel_hi:[1,1]
	v_pk_mul_f32 v[126:127], v[126:127], v[174:175] op_sel:[0,1] op_sel_hi:[1,1]
	v_cvt_pk_bf16_f32 v0, v0, v1
	v_cvt_pk_bf16_f32 v1, v2, v3
	v_cvt_pk_bf16_f32 v2, v4, v5
	v_cvt_pk_bf16_f32 v3, v6, v7
	v_cvt_pk_bf16_f32 v4, v8, v9
	v_cvt_pk_bf16_f32 v5, v10, v11
	v_cvt_pk_bf16_f32 v6, v12, v13
	v_cvt_pk_bf16_f32 v7, v14, v15
	ds_write_b16 v180, v0 offset:0
	ds_write_b16_d16_hi v180, v0 offset:144
	ds_write_b16 v180, v1 offset:288
	ds_write_b16_d16_hi v180, v1 offset:432
	ds_write_b16 v180, v2 offset:1152
	ds_write_b16_d16_hi v180, v2 offset:1296
	ds_write_b16 v180, v3 offset:1440
	ds_write_b16_d16_hi v180, v3 offset:1584
	ds_write_b16 v180, v4 offset:2304
	ds_write_b16_d16_hi v180, v4 offset:2448
	ds_write_b16 v180, v5 offset:2592
	ds_write_b16_d16_hi v180, v5 offset:2736
	ds_write_b16 v180, v6 offset:3456
	ds_write_b16_d16_hi v180, v6 offset:3600
	ds_write_b16 v180, v7 offset:3744
	ds_write_b16_d16_hi v180, v7 offset:3888
	v_cvt_pk_bf16_f32 v16, v16, v17
	v_cvt_pk_bf16_f32 v17, v18, v19
	v_cvt_pk_bf16_f32 v18, v20, v21
	v_cvt_pk_bf16_f32 v19, v22, v23
	v_cvt_pk_bf16_f32 v20, v24, v25
	v_cvt_pk_bf16_f32 v21, v26, v27
	v_cvt_pk_bf16_f32 v22, v28, v29
	v_cvt_pk_bf16_f32 v23, v30, v31
	ds_write_b16 v180, v16 offset:4608
	ds_write_b16_d16_hi v180, v16 offset:4752
	ds_write_b16 v180, v17 offset:4896
	ds_write_b16_d16_hi v180, v17 offset:5040
	ds_write_b16 v180, v18 offset:5760
	ds_write_b16_d16_hi v180, v18 offset:5904
	ds_write_b16 v180, v19 offset:6048
	ds_write_b16_d16_hi v180, v19 offset:6192
	ds_write_b16 v180, v20 offset:6912
	ds_write_b16_d16_hi v180, v20 offset:7056
	ds_write_b16 v180, v21 offset:7200
	ds_write_b16_d16_hi v180, v21 offset:7344
	ds_write_b16 v180, v22 offset:8064
	ds_write_b16_d16_hi v180, v22 offset:8208
	ds_write_b16 v180, v23 offset:8352
	ds_write_b16_d16_hi v180, v23 offset:8496
	v_cvt_pk_bf16_f32 v32, v32, v33
	v_cvt_pk_bf16_f32 v33, v34, v35
	v_cvt_pk_bf16_f32 v34, v36, v37
	v_cvt_pk_bf16_f32 v35, v38, v39
	v_cvt_pk_bf16_f32 v36, v40, v41
	v_cvt_pk_bf16_f32 v37, v42, v43
	v_cvt_pk_bf16_f32 v38, v44, v45
	v_cvt_pk_bf16_f32 v39, v46, v47
	ds_write_b16 v180, v32 offset:64
	ds_write_b16_d16_hi v180, v32 offset:208
	ds_write_b16 v180, v33 offset:352
	ds_write_b16_d16_hi v180, v33 offset:496
	ds_write_b16 v180, v34 offset:1216
	ds_write_b16_d16_hi v180, v34 offset:1360
	ds_write_b16 v180, v35 offset:1504
	ds_write_b16_d16_hi v180, v35 offset:1648
	ds_write_b16 v180, v36 offset:2368
	ds_write_b16_d16_hi v180, v36 offset:2512
	ds_write_b16 v180, v37 offset:2656
	ds_write_b16_d16_hi v180, v37 offset:2800
	ds_write_b16 v180, v38 offset:3520
	ds_write_b16_d16_hi v180, v38 offset:3664
	ds_write_b16 v180, v39 offset:3808
	ds_write_b16_d16_hi v180, v39 offset:3952
	v_cvt_pk_bf16_f32 v48, v48, v49
	v_cvt_pk_bf16_f32 v49, v50, v51
	v_cvt_pk_bf16_f32 v50, v52, v53
	v_cvt_pk_bf16_f32 v51, v54, v55
	v_cvt_pk_bf16_f32 v52, v56, v57
	v_cvt_pk_bf16_f32 v53, v58, v59
	v_cvt_pk_bf16_f32 v54, v60, v61
	v_cvt_pk_bf16_f32 v55, v62, v63
	ds_write_b16 v180, v48 offset:4672
	ds_write_b16_d16_hi v180, v48 offset:4816
	ds_write_b16 v180, v49 offset:4960
	ds_write_b16_d16_hi v180, v49 offset:5104
	ds_write_b16 v180, v50 offset:5824
	ds_write_b16_d16_hi v180, v50 offset:5968
	ds_write_b16 v180, v51 offset:6112
	ds_write_b16_d16_hi v180, v51 offset:6256
	ds_write_b16 v180, v52 offset:6976
	ds_write_b16_d16_hi v180, v52 offset:7120
	ds_write_b16 v180, v53 offset:7264
	ds_write_b16_d16_hi v180, v53 offset:7408
	ds_write_b16 v180, v54 offset:8128
	ds_write_b16_d16_hi v180, v54 offset:8272
	ds_write_b16 v180, v55 offset:8416
	ds_write_b16_d16_hi v180, v55 offset:8560
	s_waitcnt lgkmcnt(0)
	ds_read_b128 v[0:3], v198 offset:0
	ds_read_b128 v[4:7], v198 offset:1152
	ds_read_b128 v[8:11], v198 offset:2304
	ds_read_b128 v[12:15], v198 offset:3456
	ds_read_b128 v[16:19], v198 offset:4608
	ds_read_b128 v[20:23], v198 offset:5760
	ds_read_b128 v[24:27], v198 offset:6912
	ds_read_b128 v[28:31], v198 offset:8064
	s_waitcnt lgkmcnt(7)
	global_store_dwordx4 v199, v[0:3], s[38:39]
	s_add_u32 s38, s38, 0x8000
	s_addc_u32 s39, s39, 0
	s_waitcnt lgkmcnt(6)
	global_store_dwordx4 v199, v[4:7], s[38:39]
	s_add_u32 s38, s38, 0x8000
	s_addc_u32 s39, s39, 0
	s_waitcnt lgkmcnt(5)
	global_store_dwordx4 v199, v[8:11], s[38:39]
	s_add_u32 s38, s38, 0x8000
	s_addc_u32 s39, s39, 0
	s_waitcnt lgkmcnt(4)
	global_store_dwordx4 v199, v[12:15], s[38:39]
	s_add_u32 s38, s38, 0x8000
	s_addc_u32 s39, s39, 0
	s_waitcnt lgkmcnt(3)
	global_store_dwordx4 v199, v[16:19], s[38:39]
	s_add_u32 s38, s38, 0x8000
	s_addc_u32 s39, s39, 0
	s_waitcnt lgkmcnt(2)
	global_store_dwordx4 v199, v[20:23], s[38:39]
	s_add_u32 s38, s38, 0x8000
	s_addc_u32 s39, s39, 0
	s_waitcnt lgkmcnt(1)
	global_store_dwordx4 v199, v[24:27], s[38:39]
	s_add_u32 s38, s38, 0x8000
	s_addc_u32 s39, s39, 0
	s_waitcnt lgkmcnt(0)
	global_store_dwordx4 v199, v[28:31], s[38:39]
	s_sub_u32 s38, s38, 229248
	s_subb_u32 s39, s39, 0
	v_cvt_pk_bf16_f32 v64, v64, v65
	v_cvt_pk_bf16_f32 v65, v66, v67
	v_cvt_pk_bf16_f32 v66, v68, v69
	v_cvt_pk_bf16_f32 v67, v70, v71
	v_cvt_pk_bf16_f32 v68, v72, v73
	v_cvt_pk_bf16_f32 v69, v74, v75
	v_cvt_pk_bf16_f32 v70, v76, v77
	v_cvt_pk_bf16_f32 v71, v78, v79
	ds_write_b16 v180, v64 offset:0
	ds_write_b16_d16_hi v180, v64 offset:144
	ds_write_b16 v180, v65 offset:288
	ds_write_b16_d16_hi v180, v65 offset:432
	ds_write_b16 v180, v66 offset:1152
	ds_write_b16_d16_hi v180, v66 offset:1296
	ds_write_b16 v180, v67 offset:1440
	ds_write_b16_d16_hi v180, v67 offset:1584
	ds_write_b16 v180, v68 offset:2304
	ds_write_b16_d16_hi v180, v68 offset:2448
	ds_write_b16 v180, v69 offset:2592
	ds_write_b16_d16_hi v180, v69 offset:2736
	ds_write_b16 v180, v70 offset:3456
	ds_write_b16_d16_hi v180, v70 offset:3600
	ds_write_b16 v180, v71 offset:3744
	ds_write_b16_d16_hi v180, v71 offset:3888
	v_cvt_pk_bf16_f32 v80, v80, v81
	v_cvt_pk_bf16_f32 v81, v82, v83
	v_cvt_pk_bf16_f32 v82, v84, v85
	v_cvt_pk_bf16_f32 v83, v86, v87
	v_cvt_pk_bf16_f32 v84, v88, v89
	v_cvt_pk_bf16_f32 v85, v90, v91
	v_cvt_pk_bf16_f32 v86, v92, v93
	v_cvt_pk_bf16_f32 v87, v94, v95
	ds_write_b16 v180, v80 offset:4608
	ds_write_b16_d16_hi v180, v80 offset:4752
	ds_write_b16 v180, v81 offset:4896
	ds_write_b16_d16_hi v180, v81 offset:5040
	ds_write_b16 v180, v82 offset:5760
	ds_write_b16_d16_hi v180, v82 offset:5904
	ds_write_b16 v180, v83 offset:6048
	ds_write_b16_d16_hi v180, v83 offset:6192
	ds_write_b16 v180, v84 offset:6912
	ds_write_b16_d16_hi v180, v84 offset:7056
	ds_write_b16 v180, v85 offset:7200
	ds_write_b16_d16_hi v180, v85 offset:7344
	ds_write_b16 v180, v86 offset:8064
	ds_write_b16_d16_hi v180, v86 offset:8208
	ds_write_b16 v180, v87 offset:8352
	ds_write_b16_d16_hi v180, v87 offset:8496
	v_cvt_pk_bf16_f32 v96, v96, v97
	v_cvt_pk_bf16_f32 v97, v98, v99
	v_cvt_pk_bf16_f32 v98, v100, v101
	v_cvt_pk_bf16_f32 v99, v102, v103
	v_cvt_pk_bf16_f32 v100, v104, v105
	v_cvt_pk_bf16_f32 v101, v106, v107
	v_cvt_pk_bf16_f32 v102, v108, v109
	v_cvt_pk_bf16_f32 v103, v110, v111
	ds_write_b16 v180, v96 offset:64
	ds_write_b16_d16_hi v180, v96 offset:208
	ds_write_b16 v180, v97 offset:352
	ds_write_b16_d16_hi v180, v97 offset:496
	ds_write_b16 v180, v98 offset:1216
	ds_write_b16_d16_hi v180, v98 offset:1360
	ds_write_b16 v180, v99 offset:1504
	ds_write_b16_d16_hi v180, v99 offset:1648
	ds_write_b16 v180, v100 offset:2368
	ds_write_b16_d16_hi v180, v100 offset:2512
	ds_write_b16 v180, v101 offset:2656
	ds_write_b16_d16_hi v180, v101 offset:2800
	ds_write_b16 v180, v102 offset:3520
	ds_write_b16_d16_hi v180, v102 offset:3664
	ds_write_b16 v180, v103 offset:3808
	ds_write_b16_d16_hi v180, v103 offset:3952
	v_cvt_pk_bf16_f32 v112, v112, v113
	v_cvt_pk_bf16_f32 v113, v114, v115
	v_cvt_pk_bf16_f32 v114, v116, v117
	v_cvt_pk_bf16_f32 v115, v118, v119
	v_cvt_pk_bf16_f32 v116, v120, v121
	v_cvt_pk_bf16_f32 v117, v122, v123
	v_cvt_pk_bf16_f32 v118, v124, v125
	v_cvt_pk_bf16_f32 v119, v126, v127
	ds_write_b16 v180, v112 offset:4672
	ds_write_b16_d16_hi v180, v112 offset:4816
	ds_write_b16 v180, v113 offset:4960
	ds_write_b16_d16_hi v180, v113 offset:5104
	ds_write_b16 v180, v114 offset:5824
	ds_write_b16_d16_hi v180, v114 offset:5968
	ds_write_b16 v180, v115 offset:6112
	ds_write_b16_d16_hi v180, v115 offset:6256
	ds_write_b16 v180, v116 offset:6976
	ds_write_b16_d16_hi v180, v116 offset:7120
	ds_write_b16 v180, v117 offset:7264
	ds_write_b16_d16_hi v180, v117 offset:7408
	ds_write_b16 v180, v118 offset:8128
	ds_write_b16_d16_hi v180, v118 offset:8272
	ds_write_b16 v180, v119 offset:8416
	ds_write_b16_d16_hi v180, v119 offset:8560
	s_waitcnt lgkmcnt(0)
	ds_read_b128 v[64:67], v198 offset:0
	ds_read_b128 v[68:71], v198 offset:1152
	ds_read_b128 v[72:75], v198 offset:2304
	ds_read_b128 v[76:79], v198 offset:3456
	ds_read_b128 v[80:83], v198 offset:4608
	ds_read_b128 v[84:87], v198 offset:5760
	ds_read_b128 v[88:91], v198 offset:6912
	ds_read_b128 v[92:95], v198 offset:8064
	s_waitcnt lgkmcnt(7)
	global_store_dwordx4 v199, v[64:67], s[38:39]
	s_add_u32 s38, s38, 0x8000
	s_addc_u32 s39, s39, 0
	s_waitcnt lgkmcnt(6)
	global_store_dwordx4 v199, v[68:71], s[38:39]
	s_add_u32 s38, s38, 0x8000
	s_addc_u32 s39, s39, 0
	s_waitcnt lgkmcnt(5)
	global_store_dwordx4 v199, v[72:75], s[38:39]
	s_add_u32 s38, s38, 0x8000
	s_addc_u32 s39, s39, 0
	s_waitcnt lgkmcnt(4)
	global_store_dwordx4 v199, v[76:79], s[38:39]
	s_add_u32 s38, s38, 0x8000
	s_addc_u32 s39, s39, 0
	s_waitcnt lgkmcnt(3)
	global_store_dwordx4 v199, v[80:83], s[38:39]
	s_add_u32 s38, s38, 0x8000
	s_addc_u32 s39, s39, 0
	s_waitcnt lgkmcnt(2)
	global_store_dwordx4 v199, v[84:87], s[38:39]
	s_add_u32 s38, s38, 0x8000
	s_addc_u32 s39, s39, 0
	s_waitcnt lgkmcnt(1)
	global_store_dwordx4 v199, v[88:91], s[38:39]
	s_add_u32 s38, s38, 0x8000
	s_addc_u32 s39, s39, 0
	s_waitcnt lgkmcnt(0)
	global_store_dwordx4 v199, v[92:95], s[38:39]

.LBB0_189:
	s_waitcnt vmcnt(0)
	s_barrier
	s_mov_b64 s[0:1], exec
	v_readlane_b32 s2, v254, 23
	v_readlane_b32 s3, v254, 24
	s_and_b64 s[2:3], s[0:1], s[2:3]
	s_mov_b64 exec, s[2:3]
	s_cbranch_execz .LBB0_241
	v_readlane_b32 s74, v255, 50
	v_readlane_b32 s75, v255, 51
	v_mov_b32_e32 v0, 0x24000
	s_nop 3
	v_mov_b32_e32 v2, s74
	v_mov_b32_e32 v1, s75
	ds_write_b32 v0, v2
	ds_write_b32 v0, v1 offset:4
	s_waitcnt lgkmcnt(0)
	v_mov_b32_e32 v0, 0x24000
	s_waitcnt vmcnt(0) expcnt(0) lgkmcnt(0)
	ds_read_b32 v2, v0
	v_mov_b32_e32 v0, 0x24004
	ds_read_b32 v0, v0
	s_waitcnt lgkmcnt(1)
	v_cmp_ne_u32_e32 vcc, 0, v2
	s_cbranch_vccnz .LBB0_205
	v_readlane_b32 s2, v254, 2
	v_readlane_b32 s36, v254, 0
	s_mul_i32 s33, s91, s2
	v_readlane_b32 s37, v254, 1
	s_add_u32 s2, s36, 0x1ae20200
	s_addc_u32 s3, s37, 0
	s_add_u32 s4, s36, 0x1ae20400
	s_addc_u32 s5, s37, 0
	s_add_u32 s6, s36, 0x1ae20500
	s_addc_u32 s7, s37, 0
	s_add_u32 s8, s36, 0x1ae20600
	s_addc_u32 s9, s37, 0
	s_add_u32 s10, s36, 0x1ae20700
	s_addc_u32 s11, s37, 0
	s_add_u32 s12, s36, 0x1ae20800
	s_addc_u32 s13, s37, 0
	s_add_u32 s14, s36, 0x1ae20900
	s_addc_u32 s15, s37, 0
	s_add_u32 s16, s36, 0x1ae20a00
	s_addc_u32 s17, s37, 0
	s_add_u32 s18, s36, 0x1ae20b00
	s_addc_u32 s19, s37, 0
	s_add_u32 s20, s36, 0x1ae20c00
	s_addc_u32 s21, s37, 0
	s_add_u32 s22, s36, 0x1ae20d00
	s_addc_u32 s23, s37, 0
	s_add_u32 s24, s36, 0x1ae20e00
	s_addc_u32 s25, s37, 0
	s_add_u32 s26, s36, 0x1ae20f00
	s_addc_u32 s27, s37, 0
	s_add_u32 s28, s36, 0x1ae21000
	s_addc_u32 s29, s37, 0
	s_add_u32 s30, s36, 0x1ae21100
	s_addc_u32 s31, s37, 0
	s_add_u32 s34, s36, 0x1ae21200
	s_addc_u32 s35, s37, 0
	s_add_u32 s36, s36, 0x1ae21300
	s_mul_i32 s33, s33, s90
	s_addc_u32 s37, s37, 0
	s_mov_b32 s44, 1
	v_mov_b32_e32 v16, 0
	s_branch .LBB0_193

.LBB0_721:
	s_or_b64 exec, exec, s[0:1]
	v_readlane_b32 s2, v254, 41
	v_readlane_b32 s3, v254, 42
	v_mov_b32_e32 v176, v178
	s_mov_b64 s[0:1], 0
	s_andn2_b64 vcc, exec, s[2:3]
	s_waitcnt lgkmcnt(0)
	s_barrier
	s_cbranch_vccnz .LBB0_774
	v_readlane_b32 s2, v254, 0
	v_readlane_b32 s3, v254, 1
	s_add_u32 s4, s2, s0
	s_addc_u32 s5, s3, s1
	s_add_u32 s21, s4, 0xa120000
	s_addc_u32 s47, s5, 0
	s_add_u32 s60, s4, 0x880000
	v_and_b32_e32 v0, 63, v176
	v_lshlrev_b32_e32 v3, 8, v176
	v_lshlrev_b32_e32 v4, 4, v176
	s_movk_i32 s6, 0x70
	s_addc_u32 s61, s5, 0
	v_and_b32_e32 v3, 0x3800, v3
	v_bitop3_b32 v0, v0, s6, v4 bitop3:0x48
	s_add_u32 s0, s4, 0x14920000
	v_and_b32_e32 v1, 31, v176
	v_bfe_u32 v2, v176, 5, 1
	v_or_b32_e32 v177, v0, v3
	v_bitop3_b32 v185, v0, 64, v3 bitop3:0x36
	v_lshrrev_b32_e32 v0, 1, v176
	s_mov_b32 s6, 0x1ffff80
	s_addc_u32 s1, s5, 0
	v_bfe_u32 v3, v176, 1, 3
	v_and_or_b32 v1, v0, s6, v1
	v_bitop3_b32 v0, v2, v0, 7 bitop3:0x78
	s_add_u32 s2, s4, 0x1ad20000
	v_lshlrev_b32_e32 v188, 4, v0
	v_bitop3_b32 v0, v2, v3, 2 bitop3:0x36
	s_addc_u32 s3, s5, 0
	v_lshlrev_b32_e32 v189, 4, v0
	v_bitop3_b32 v0, v2, v3, 4 bitop3:0x36
	s_add_u32 s8, s4, 0x1ada0000
	v_lshlrev_b32_e32 v190, 4, v0
	v_bitop3_b32 v0, v2, v3, 6 bitop3:0x36
	s_addc_u32 s9, s5, 0
	v_lshlrev_b32_e32 v191, 4, v0
	v_and_b32_e32 v0, 64, v179
	s_add_u32 s10, s4, 0x1ade0000
	v_add_u32_e32 v0, 64, v0
	s_addc_u32 s11, s5, 0
	v_lshlrev_b32_e32 v186, 7, v1
	v_lshlrev_b32_e32 v1, 7, v176
	v_cmp_lt_i32_e32 vcc, v184, v0
	v_and_b32_e32 v187, 0x6f80, v1
	s_add_u32 s12, s4, 0xc120008
	v_cndmask_b32_e32 v1, v179, v184, vcc
	v_cmp_lt_i32_e32 vcc, v183, v0
	v_lshlrev_b32_e32 v184, 2, v1
	s_addc_u32 s13, s5, 0
	v_cndmask_b32_e32 v1, v179, v183, vcc
	v_cmp_lt_i32_e32 vcc, v182, v0
	s_lshl_b32 s62, s88, 2
	s_lshl_b32 s63, s90, 2
	v_cndmask_b32_e32 v0, v179, v182, vcc
	s_add_u32 s14, s4, 0xc120108
	s_movk_i32 s18, 0xfe00
	v_lshlrev_b32_e32 v183, 2, v1
	v_lshlrev_b32_e32 v182, 2, v0
	s_addc_u32 s15, s5, 0
	s_mov_b32 s17, 0
	s_movk_i32 s64, 0x410
	v_mov_b32_e32 v145, 0
	s_movk_i32 s65, 0x1c0
	s_mov_b32 s19, -1
	v_mov_b32_e32 v192, 0x358637bd
	s_mov_b32 s66, 0x800000
	s_movk_i32 s67, 0x2200
	s_mov_b32 s20, 0x3e000000
	s_mov_b64 s[22:23], 0x44000
	v_mov_b32_e32 v193, 0x20800
	v_readlane_b32 s85, v254, 22
	s_mov_b32 s80, 0
	s_mov_b32 s56, 0
	s_mov_b32 s57, 0x20000
	v_mov_b32_e32 v194, 0x24000
	ds_read_b32 v198, v194
	ds_read_b32 v199, v194 offset:4
	s_waitcnt lgkmcnt(0)
	v_readfirstlane_b32 s74, v198
	v_readfirstlane_b32 s75, v199
	s_nop 3
	v_writelane_b32 v255, s74, 50
	v_writelane_b32 v255, s75, 51
	s_mov_b32 s86, s88
	s_branch .LBB0_724

.LBB0_725:
	v_add_u32_e32 v162, v166, v189
	v_add_u32_e32 v167, v144, v189
	s_waitcnt lgkmcnt(2)
	v_mfma_f32_32x32x16_bf16 v[0:15], v[128:131], v[132:135], v[0:15]
	ds_read_b128 v[154:157], v162
	s_add_u32 s4, s4, 0x80
	s_addc_u32 s5, s5, 0
	s_add_i32 s45, s45, 1
	s_cmpk_lg_i32 s4, 0x800
	s_mov_b32 s46, s50
	v_mfma_f32_32x32x16_bf16 v[16:31], v[150:153], v[132:135], v[16:31]
	ds_read_b128 v[132:135], v162 offset:4096
	s_waitcnt lgkmcnt(4)
	v_mfma_f32_32x32x16_bf16 v[32:47], v[128:131], v[136:139], v[32:47]
	ds_read_b128 v[158:161], v162 offset:8192
	v_mfma_f32_32x32x16_bf16 v[48:63], v[150:153], v[136:139], v[48:63]
	ds_read_b128 v[136:139], v162 offset:12288
	s_waitcnt lgkmcnt(5)
	v_mfma_f32_32x32x16_bf16 v[64:79], v[128:131], v[140:143], v[64:79]
	ds_read_b128 v[162:165], v167 offset:32768
	v_mfma_f32_32x32x16_bf16 v[80:95], v[150:153], v[140:143], v[80:95]
	ds_read_b128 v[140:143], v167 offset:36864
	v_add_u32_e32 v167, v166, v190
	s_waitcnt lgkmcnt(6)
	v_mfma_f32_32x32x16_bf16 v[96:111], v[128:131], v[146:149], v[96:111]
	v_mfma_f32_32x32x16_bf16 v[112:127], v[150:153], v[146:149], v[112:127]
	s_waitcnt lgkmcnt(1)
	v_mfma_f32_32x32x16_bf16 v[0:15], v[162:165], v[154:157], v[0:15]
	ds_read_b128 v[128:131], v167
	s_waitcnt lgkmcnt(1)
	v_mfma_f32_32x32x16_bf16 v[16:31], v[140:143], v[154:157], v[16:31]
	ds_read_b128 v[146:149], v167 offset:4096
	v_mfma_f32_32x32x16_bf16 v[32:47], v[162:165], v[132:135], v[32:47]
	ds_read_b128 v[150:153], v167 offset:8192
	v_mfma_f32_32x32x16_bf16 v[48:63], v[140:143], v[132:135], v[48:63]
	ds_read_b128 v[132:135], v167 offset:12288
	v_add_u32_e32 v167, v144, v190
	v_add_u32_e32 v144, v144, v191
	v_mfma_f32_32x32x16_bf16 v[64:79], v[162:165], v[158:161], v[64:79]
	ds_read_b128 v[154:157], v167 offset:32768
	v_mfma_f32_32x32x16_bf16 v[80:95], v[140:143], v[158:161], v[80:95]
	ds_read_b128 v[158:161], v167 offset:36864
	v_mfma_f32_32x32x16_bf16 v[96:111], v[162:165], v[136:139], v[96:111]
	v_add_u32_e32 v162, v166, v191
	v_mfma_f32_32x32x16_bf16 v[112:127], v[140:143], v[136:139], v[112:127]
	s_waitcnt lgkmcnt(1)
	v_mfma_f32_32x32x16_bf16 v[0:15], v[154:157], v[128:131], v[0:15]
	ds_read_b128 v[136:139], v162
	s_waitcnt lgkmcnt(1)
	v_mfma_f32_32x32x16_bf16 v[16:31], v[158:161], v[128:131], v[16:31]
	ds_read_b128 v[128:131], v162 offset:4096
	v_mfma_f32_32x32x16_bf16 v[32:47], v[154:157], v[146:149], v[32:47]
	ds_read_b128 v[140:143], v162 offset:8192
	v_mfma_f32_32x32x16_bf16 v[48:63], v[158:161], v[146:149], v[48:63]
	ds_read_b128 v[146:149], v162 offset:12288
	v_mfma_f32_32x32x16_bf16 v[64:79], v[154:157], v[150:153], v[64:79]
	ds_read_b128 v[162:165], v144 offset:32768
	v_mfma_f32_32x32x16_bf16 v[80:95], v[158:161], v[150:153], v[80:95]
	ds_read_b128 v[150:153], v144 offset:36864
	v_mfma_f32_32x32x16_bf16 v[96:111], v[154:157], v[132:135], v[96:111]
	v_mfma_f32_32x32x16_bf16 v[112:127], v[158:161], v[132:135], v[112:127]
	s_waitcnt lgkmcnt(0)
	s_cbranch_scc0 .Lxt_L1
	s_cmp_lt_u32 s45, 15
	s_cbranch_scc0 .Lxr_w0_L1
	s_waitcnt vmcnt(4)
	s_branch .Lxr_wb_L1

.Lxr_wb_L1:
	s_barrier
	s_and_b32 s6, s46, 0x10000
	v_or_b32_e32 v144, s6, v187
	v_add_u32_e32 v194, v144, v188
	v_add_u32_e32 v166, s56, v186
	v_add_u32_e32 v195, v166, v188
	ds_read_b128 v[132:135], v195
	v_mfma_f32_32x32x16_bf16 v[16:31], v[150:153], v[136:139], v[16:31]
	v_mfma_f32_32x32x16_bf16 v[48:63], v[150:153], v[128:131], v[48:63]
	v_mfma_f32_32x32x16_bf16 v[80:95], v[150:153], v[140:143], v[80:95]
	v_mfma_f32_32x32x16_bf16 v[112:127], v[150:153], v[146:149], v[112:127]
	ds_read_b128 v[150:153], v194 offset:36864
	v_mfma_f32_32x32x16_bf16 v[0:15], v[162:165], v[136:139], v[0:15]
	ds_read_b128 v[136:139], v195 offset:4096
	v_mfma_f32_32x32x16_bf16 v[32:47], v[162:165], v[128:131], v[32:47]
	ds_read_b128 v[128:131], v194 offset:32768
	v_mfma_f32_32x32x16_bf16 v[64:79], v[162:165], v[140:143], v[64:79]
	ds_read_b128 v[140:143], v195 offset:8192
	v_mfma_f32_32x32x16_bf16 v[96:111], v[162:165], v[146:149], v[96:111]
	ds_read_b128 v[146:149], v195 offset:12288
	s_add_i32 s50, s46, 0x10000
	s_cmp_lt_u32 s45, 15
	s_cbranch_scc0 .Lxr_ni_L1s
	s_add_u32 s82, s4, s81
	s_addk_i32 s82, 0x80
	s_and_b32 s82, s82, 0x7ff
	s_cmp_eq_u32 s45, 0
	s_cbranch_scc0 .Lxr_n1_L1s
	s_add_u32 s74, s56, s57
	s_sub_u32 s74, 0x30000, s74
	s_add_u32 s74, s74, s26
	s_add_u32 s6, s43, s82
	s_addc_u32 s7, s44, 0
	s_add_u32 s75, s74, 0x0
	s_mov_b32 m0, s75
	global_load_lds_dwordx4 v177, s[6:7]
	s_add_u32 s6, s41, s82
	s_addc_u32 s7, s42, 0
	s_add_u32 s75, s74, 0x400
	s_mov_b32 m0, s75
	global_load_lds_dwordx4 v185, s[6:7]
	s_add_u32 s6, s39, s82
	s_addc_u32 s7, s40, 0
	s_add_u32 s75, s74, 0x800
	s_mov_b32 m0, s75
	global_load_lds_dwordx4 v177, s[6:7]
	s_add_u32 s6, s37, s82
	s_addc_u32 s7, s38, 0
	s_add_u32 s75, s74, 0xc00
	s_mov_b32 m0, s75
	global_load_lds_dwordx4 v185, s[6:7]
.Lxr_n1_L1s:
	s_and_b32 s74, s50, 0x10000
	s_add_u32 s74, s74, s26
	s_add_u32 s74, s74, 0x8000
	s_add_u32 s6, s35, s82
	s_addc_u32 s7, s36, 0
	s_add_u32 s75, s74, 0x0
	s_mov_b32 m0, s75
	global_load_lds_dwordx4 v177, s[6:7]
	s_add_u32 s6, s31, s82
	s_addc_u32 s7, s34, 0
	s_add_u32 s75, s74, 0x400
	s_mov_b32 m0, s75
	global_load_lds_dwordx4 v185, s[6:7]
	s_add_u32 s6, s29, s82
	s_addc_u32 s7, s30, 0
	s_add_u32 s75, s74, 0x800
	s_mov_b32 m0, s75
	global_load_lds_dwordx4 v177, s[6:7]
	s_add_u32 s6, s27, s82
	s_addc_u32 s7, s28, 0
	s_add_u32 s75, s74, 0xc00
	s_mov_b32 m0, s75
	global_load_lds_dwordx4 v185, s[6:7]
	s_cmp_lt_u32 s45, 14
	s_cbranch_scc0 .Lxr_ni_L1s
	s_addk_i32 s82, 0x80
	s_and_b32 s82, s82, 0x7ff
	s_add_u32 s74, s57, s26
	s_add_u32 s6, s43, s82
	s_addc_u32 s7, s44, 0
	s_add_u32 s75, s74, 0x0
	s_mov_b32 m0, s75
	global_load_lds_dwordx4 v177, s[6:7]
	s_add_u32 s6, s41, s82
	s_addc_u32 s7, s42, 0
	s_add_u32 s75, s74, 0x400
	s_mov_b32 m0, s75
	global_load_lds_dwordx4 v185, s[6:7]
	s_add_u32 s6, s39, s82
	s_addc_u32 s7, s40, 0
	s_add_u32 s75, s74, 0x800
	s_mov_b32 m0, s75
	global_load_lds_dwordx4 v177, s[6:7]
	s_add_u32 s6, s37, s82
	s_addc_u32 s7, s38, 0
	s_add_u32 s75, s74, 0xc00
	s_mov_b32 m0, s75
	global_load_lds_dwordx4 v185, s[6:7]

.Lkin_L1:
	s_and_b32 s6, s46, 0x10000
	v_or_b32_e32 v144, s6, v187
	v_add_u32_e32 v194, v144, v188
	v_add_u32_e32 v166, s56, v186
	v_add_u32_e32 v195, v166, v188
	ds_read_b128 v[132:135], v195
	ds_read_b128 v[150:153], v194 offset:36864
	ds_read_b128 v[136:139], v195 offset:4096
	ds_read_b128 v[128:131], v194 offset:32768
	ds_read_b128 v[140:143], v195 offset:8192
	ds_read_b128 v[146:149], v195 offset:12288
	s_add_i32 s50, s46, 0x10000
	s_cmp_lt_u32 s45, 15
	s_cbranch_scc0 .Lxr_ni_L1e
	s_add_u32 s82, s4, s81
	s_addk_i32 s82, 0x80
	s_and_b32 s82, s82, 0x7ff
	s_cmp_eq_u32 s45, 0
	s_cbranch_scc0 .Lxr_n1_L1e
	s_add_u32 s74, s56, s57
	s_sub_u32 s74, 0x30000, s74
	s_add_u32 s74, s74, s26
	s_add_u32 s6, s43, s82
	s_addc_u32 s7, s44, 0
	s_add_u32 s75, s74, 0x0
	s_mov_b32 m0, s75
	global_load_lds_dwordx4 v177, s[6:7]
	s_add_u32 s6, s41, s82
	s_addc_u32 s7, s42, 0
	s_add_u32 s75, s74, 0x400
	s_mov_b32 m0, s75
	global_load_lds_dwordx4 v185, s[6:7]
	s_add_u32 s6, s39, s82
	s_addc_u32 s7, s40, 0
	s_add_u32 s75, s74, 0x800
	s_mov_b32 m0, s75
	global_load_lds_dwordx4 v177, s[6:7]
	s_add_u32 s6, s37, s82
	s_addc_u32 s7, s38, 0
	s_add_u32 s75, s74, 0xc00
	s_mov_b32 m0, s75
	global_load_lds_dwordx4 v185, s[6:7]

.Lpe_notv_L1:
	s_cmp_ge_u32 s25, 9
	s_cbranch_scc1 .Lpe_gates_L1
	s_lshr_b32 s34, s25, 1
	s_cmp_ge_u32 s25, 6
	s_cselect_b32 s35, 1, 0
	s_sub_u32 s34, s34, s35
	s_lshl_b32 s35, s98, 2
	s_add_u32 s35, s35, s34
	s_lshl_b32 s35, s35, 8
	v_readlane_b32 s82, v254, 14
	v_readlane_b32 s83, v254, 15
	s_add_u32 s82, s82, s35
	s_addc_u32 s83, s83, 0
	global_load_dwordx4 v[198:201], v146, s[82:83] offset:0
	global_load_dwordx4 v[202:205], v146, s[82:83] offset:32
	global_load_dwordx4 v[206:209], v146, s[82:83] offset:64
	global_load_dwordx4 v[210:213], v146, s[82:83] offset:96
	global_load_dwordx4 v[214:217], v146, s[82:83] offset:128
	global_load_dwordx4 v[218:221], v146, s[82:83] offset:160
	global_load_dwordx4 v[222:225], v146, s[82:83] offset:192
	global_load_dwordx4 v[226:229], v146, s[82:83] offset:224
	s_and_b32 s35, s34, 1
	s_cmp_eq_u32 s35, 0
	s_cselect_b32 s36, 0x3e000000, 1.0
	s_and_b32 s35, s29, 0x7ff
	s_lshl_b32 s35, s35, 7
	s_add_u32 s96, s72, 0x1ada0000
	s_addc_u32 s97, s73, 0
	s_add_u32 s96, s96, s35
	s_addc_u32 s97, s97, 0
	s_add_u32 s100, s96, 0x40000
	s_addc_u32 s101, s97, 0
	s_cmp_ge_u32 s34, 2
	s_cselect_b32 s37, 1, 0
	s_waitcnt vmcnt(8)
	v_lshlrev_b32_e32 v180, 7, v197
	v_add_u32_e32 v180, v180, v146
	v_mov_b32_e32 v197, 0x358637bd
	v_pk_add_f32 v[128:129], v[128:129], v[130:131]
	v_pk_add_f32 v[132:133], v[132:133], v[134:135]
	v_pk_add_f32 v[136:137], v[136:137], v[138:139]
	v_pk_add_f32 v[140:141], v[140:141], v[142:143]
	v_pk_add_f32 v[164:165], v[164:165], v[166:167]
	v_pk_add_f32 v[168:169], v[168:169], v[170:171]
	v_pk_add_f32 v[246:247], v[246:247], v[248:249]
	v_pk_add_f32 v[250:251], v[250:251], v[252:253]
	v_pk_add_f32 v[128:129], v[128:129], v[132:133]
	v_pk_add_f32 v[136:137], v[136:137], v[140:141]
	v_pk_add_f32 v[164:165], v[164:165], v[168:169]
	v_pk_add_f32 v[246:247], v[246:247], v[250:251]
	v_add_f32_e32 v128, v128, v129
	v_add_f32_e32 v136, v136, v137
	v_add_f32_e32 v164, v164, v165
	v_add_f32_e32 v246, v246, v247
	v_fmamk_f32 v128, v128, 0x3a800000, v197
	v_fmamk_f32 v136, v136, 0x3a800000, v197
	v_fmamk_f32 v164, v164, 0x3a800000, v197
	v_fmamk_f32 v246, v246, 0x3a800000, v197
	v_rsq_f32_e32 v172, v128
	v_rsq_f32_e32 v173, v136
	v_rsq_f32_e32 v174, v164
	v_rsq_f32_e32 v175, v246
	s_nop 0
	s_add_u32 s76, s99, s90
	s_cmp_lt_u32 s76, 0x440
	s_cselect_b32 s80, 1, 0
	s_cselect_b32 s83, 0x200000, 0
	s_lshl_b32 s76, s24, 19
	s_lshl_b32 s77, s26, 16
	s_add_u32 s76, s76, s77
	s_and_b32 s77, s24, 7
	s_lshl_b32 s77, s77, 8
	s_add_u32 s76, s76, s77
	s_add_u32 s78, s72, 0xa120000
	s_addc_u32 s79, s73, 0
	s_add_u32 s78, s78, s76
	s_addc_u32 s79, s79, 0
	s_lshl_b32 s76, s25, 19
	s_add_u32 s76, s76, s83
	s_add_u32 s76, s76, s77
	s_lshl_b32 s77, s26, 16
	s_add_u32 s76, s76, s77
	s_add_u32 s82, s72, 0x880000
	s_addc_u32 s83, s73, 0
	s_add_u32 s82, s82, s76
	s_addc_u32 s83, s83, 0
	s_lshl_b32 s76, s26, 12
	s_add_u32 s76, s76, s56
	s_mov_b32 m0, s76
	s_nop 0
	global_load_lds_dwordx4 v177, s[78:79]
	s_add_u32 s78, s78, 0x4000
	s_addc_u32 s79, s79, 0
	s_add_u32 s76, s76, 0x400
	s_mov_b32 m0, s76
	s_nop 0
	global_load_lds_dwordx4 v185, s[78:79]
	s_add_u32 s78, s78, 0x4000
	s_addc_u32 s79, s79, 0
	s_add_u32 s76, s76, 0x400
	s_mov_b32 m0, s76
	s_nop 0
	global_load_lds_dwordx4 v177, s[78:79]
	s_add_u32 s78, s78, 0x4000
	s_addc_u32 s79, s79, 0
	s_add_u32 s76, s76, 0x400
	s_mov_b32 m0, s76
	s_nop 0
	global_load_lds_dwordx4 v185, s[78:79]
	s_add_u32 s78, s78, 0x4000
	s_addc_u32 s79, s79, 0
	s_add_u32 s76, s76, 0x400
	s_sub_u32 s76, s76, s56
	s_add_u32 s76, s76, 0x7000
	s_mov_b32 m0, s76
	s_nop 0
	global_load_lds_dwordx4 v177, s[82:83]
	s_add_u32 s82, s82, 0x4000
	s_addc_u32 s83, s83, 0
	s_add_u32 s76, s76, 0x400
	s_mov_b32 m0, s76
	s_nop 0
	global_load_lds_dwordx4 v185, s[82:83]
	s_add_u32 s82, s82, 0x4000
	s_addc_u32 s83, s83, 0
	s_add_u32 s76, s76, 0x400
	s_mov_b32 m0, s76
	s_nop 0
	global_load_lds_dwordx4 v177, s[82:83]
	s_add_u32 s82, s82, 0x4000
	s_addc_u32 s83, s83, 0
	s_add_u32 s76, s76, 0x400
	s_mov_b32 m0, s76
	s_nop 0
	global_load_lds_dwordx4 v185, s[82:83]
	s_add_u32 s82, s82, 0x4000
	s_addc_u32 s83, s83, 0
	s_add_u32 s76, s76, 0x400
	s_cmp_eq_u32 s37, 0
	s_cbranch_scc1 .Lpe_norope_ld_L1
	global_load_dwordx4 v[230:233], v180, s[96:97] offset:0
	global_load_dwordx4 v[234:237], v180, s[96:97] offset:32
	global_load_dwordx4 v[238:241], v180, s[96:97] offset:64
	global_load_dwordx4 v[242:245], v180, s[96:97] offset:96
	global_load_dwordx4 v[148:151], v180, s[100:101] offset:0
	global_load_dwordx4 v[152:155], v180, s[100:101] offset:32
	global_load_dwordx4 v[156:159], v180, s[100:101] offset:64
	global_load_dwordx4 v[160:163], v180, s[100:101] offset:96

.Lpe_gates_L1:
	s_lshl_b32 s35, s98, 11
	s_add_u32 s35, s35, s30
	s_sub_u32 s35, s35, 0x900
	s_lshl_b32 s35, s35, 2
	v_readlane_b32 s82, v254, 12
	v_readlane_b32 s83, v254, 13
	s_add_u32 s82, s82, s35
	s_addc_u32 s83, s83, 0
	global_load_dwordx4 v[198:201], v146, s[82:83] offset:0
	global_load_dwordx4 v[202:205], v146, s[82:83] offset:32
	global_load_dwordx4 v[206:209], v146, s[82:83] offset:64
	global_load_dwordx4 v[210:213], v146, s[82:83] offset:96
	global_load_dwordx4 v[214:217], v146, s[82:83] offset:128
	global_load_dwordx4 v[218:221], v146, s[82:83] offset:160
	global_load_dwordx4 v[222:225], v146, s[82:83] offset:192
	global_load_dwordx4 v[226:229], v146, s[82:83] offset:224
	s_waitcnt vmcnt(8)
	v_mov_b32_e32 v197, 0x358637bd
	v_pk_add_f32 v[128:129], v[128:129], v[130:131]
	v_pk_add_f32 v[132:133], v[132:133], v[134:135]
	v_pk_add_f32 v[136:137], v[136:137], v[138:139]
	v_pk_add_f32 v[140:141], v[140:141], v[142:143]
	v_pk_add_f32 v[164:165], v[164:165], v[166:167]
	v_pk_add_f32 v[168:169], v[168:169], v[170:171]
	v_pk_add_f32 v[246:247], v[246:247], v[248:249]
	v_pk_add_f32 v[250:251], v[250:251], v[252:253]
	v_pk_add_f32 v[128:129], v[128:129], v[132:133]
	v_pk_add_f32 v[136:137], v[136:137], v[140:141]
	v_pk_add_f32 v[164:165], v[164:165], v[168:169]
	v_pk_add_f32 v[246:247], v[246:247], v[250:251]
	v_add_f32_e32 v128, v128, v129
	v_add_f32_e32 v136, v136, v137
	v_add_f32_e32 v164, v164, v165
	v_add_f32_e32 v246, v246, v247
	v_fmamk_f32 v128, v128, 0x3a800000, v197
	v_fmamk_f32 v136, v136, 0x3a800000, v197
	v_fmamk_f32 v164, v164, 0x3a800000, v197
	v_fmamk_f32 v246, v246, 0x3a800000, v197
	v_rsq_f32_e32 v172, v128
	v_rsq_f32_e32 v173, v136
	v_rsq_f32_e32 v174, v164
	v_rsq_f32_e32 v175, v246
	s_nop 0
	s_add_u32 s76, s99, s90
	s_cmp_lt_u32 s76, 0x440
	s_cselect_b32 s80, 1, 0
	s_cselect_b32 s83, 0x200000, 0
	s_lshl_b32 s76, s24, 19
	s_lshl_b32 s77, s26, 16
	s_add_u32 s76, s76, s77
	s_and_b32 s77, s24, 7
	s_lshl_b32 s77, s77, 8
	s_add_u32 s76, s76, s77
	s_add_u32 s78, s72, 0xa120000
	s_addc_u32 s79, s73, 0
	s_add_u32 s78, s78, s76
	s_addc_u32 s79, s79, 0
	s_lshl_b32 s76, s25, 19
	s_add_u32 s76, s76, s83
	s_add_u32 s76, s76, s77
	s_lshl_b32 s77, s26, 16
	s_add_u32 s76, s76, s77
	s_add_u32 s82, s72, 0x880000
	s_addc_u32 s83, s73, 0
	s_add_u32 s82, s82, s76
	s_addc_u32 s83, s83, 0
	s_lshl_b32 s76, s26, 12
	s_add_u32 s76, s76, s56
	s_mov_b32 m0, s76
	s_nop 0
	global_load_lds_dwordx4 v177, s[78:79]
	s_add_u32 s78, s78, 0x4000
	s_addc_u32 s79, s79, 0
	s_add_u32 s76, s76, 0x400
	s_mov_b32 m0, s76
	s_nop 0
	global_load_lds_dwordx4 v185, s[78:79]
	s_add_u32 s78, s78, 0x4000
	s_addc_u32 s79, s79, 0
	s_add_u32 s76, s76, 0x400
	s_mov_b32 m0, s76
	s_nop 0
	global_load_lds_dwordx4 v177, s[78:79]
	s_add_u32 s78, s78, 0x4000
	s_addc_u32 s79, s79, 0
	s_add_u32 s76, s76, 0x400
	s_mov_b32 m0, s76
	s_nop 0
	global_load_lds_dwordx4 v185, s[78:79]
	s_add_u32 s78, s78, 0x4000
	s_addc_u32 s79, s79, 0
	s_add_u32 s76, s76, 0x400
	s_sub_u32 s76, s76, s56
	s_add_u32 s76, s76, 0x7000
	s_mov_b32 m0, s76
	s_nop 0
	global_load_lds_dwordx4 v177, s[82:83]
	s_add_u32 s82, s82, 0x4000
	s_addc_u32 s83, s83, 0
	s_add_u32 s76, s76, 0x400
	s_mov_b32 m0, s76
	s_nop 0
	global_load_lds_dwordx4 v185, s[82:83]
	s_add_u32 s82, s82, 0x4000
	s_addc_u32 s83, s83, 0
	s_add_u32 s76, s76, 0x400
	s_mov_b32 m0, s76
	s_nop 0
	global_load_lds_dwordx4 v177, s[82:83]
	s_add_u32 s82, s82, 0x4000
	s_addc_u32 s83, s83, 0
	s_add_u32 s76, s76, 0x400
	s_mov_b32 m0, s76
	s_nop 0
	global_load_lds_dwordx4 v185, s[82:83]
	s_add_u32 s82, s82, 0x4000
	s_addc_u32 s83, s83, 0
	s_add_u32 s76, s76, 0x400
	v_mul_f32_e32 v172, 0xbfb8aa3b, v172
	v_mul_f32_e32 v173, 0xbfb8aa3b, v173
	v_mul_f32_e32 v174, 0xbfb8aa3b, v174
	v_mul_f32_e32 v175, 0xbfb8aa3b, v175
	s_waitcnt vmcnt(8)
	v_mul_f32_e32 v198, 0xbfb8aa3b, v198
	v_mul_f32_e32 v199, 0xbfb8aa3b, v199
	v_mul_f32_e32 v200, 0xbfb8aa3b, v200
	v_mul_f32_e32 v201, 0xbfb8aa3b, v201
	v_mul_f32_e32 v202, 0xbfb8aa3b, v202
	v_mul_f32_e32 v203, 0xbfb8aa3b, v203
	v_mul_f32_e32 v204, 0xbfb8aa3b, v204
	v_mul_f32_e32 v205, 0xbfb8aa3b, v205
	v_mul_f32_e32 v206, 0xbfb8aa3b, v206
	v_mul_f32_e32 v207, 0xbfb8aa3b, v207
	v_mul_f32_e32 v208, 0xbfb8aa3b, v208
	v_mul_f32_e32 v209, 0xbfb8aa3b, v209
	v_mul_f32_e32 v210, 0xbfb8aa3b, v210
	v_mul_f32_e32 v211, 0xbfb8aa3b, v211
	v_mul_f32_e32 v212, 0xbfb8aa3b, v212
	v_mul_f32_e32 v213, 0xbfb8aa3b, v213
	v_mul_f32_e32 v214, 0xbfb8aa3b, v214
	v_mul_f32_e32 v215, 0xbfb8aa3b, v215
	v_mul_f32_e32 v216, 0xbfb8aa3b, v216
	v_mul_f32_e32 v217, 0xbfb8aa3b, v217
	v_mul_f32_e32 v218, 0xbfb8aa3b, v218
	v_mul_f32_e32 v219, 0xbfb8aa3b, v219
	v_mul_f32_e32 v220, 0xbfb8aa3b, v220
	v_mul_f32_e32 v221, 0xbfb8aa3b, v221
	v_mul_f32_e32 v222, 0xbfb8aa3b, v222
	v_mul_f32_e32 v223, 0xbfb8aa3b, v223
	v_mul_f32_e32 v224, 0xbfb8aa3b, v224
	v_mul_f32_e32 v225, 0xbfb8aa3b, v225
	v_mul_f32_e32 v226, 0xbfb8aa3b, v226
	v_mul_f32_e32 v227, 0xbfb8aa3b, v227
	v_mul_f32_e32 v228, 0xbfb8aa3b, v228
	v_mul_f32_e32 v229, 0xbfb8aa3b, v229
	v_pk_fma_f32 v[0:1], v[0:1], v[172:173], v[198:199] op_sel_hi:[1,0,1]
	v_pk_fma_f32 v[2:3], v[2:3], v[172:173], v[200:201] op_sel_hi:[1,0,1]
	v_pk_fma_f32 v[4:5], v[4:5], v[172:173], v[202:203] op_sel_hi:[1,0,1]
	v_pk_fma_f32 v[6:7], v[6:7], v[172:173], v[204:205] op_sel_hi:[1,0,1]
	v_pk_fma_f32 v[8:9], v[8:9], v[172:173], v[206:207] op_sel_hi:[1,0,1]
	v_pk_fma_f32 v[10:11], v[10:11], v[172:173], v[208:209] op_sel_hi:[1,0,1]
	v_pk_fma_f32 v[12:13], v[12:13], v[172:173], v[210:211] op_sel_hi:[1,0,1]
	v_pk_fma_f32 v[14:15], v[14:15], v[172:173], v[212:213] op_sel_hi:[1,0,1]
	v_pk_fma_f32 v[16:17], v[16:17], v[172:173], v[214:215] op_sel_hi:[1,0,1]
	v_pk_fma_f32 v[18:19], v[18:19], v[172:173], v[216:217] op_sel_hi:[1,0,1]
	v_pk_fma_f32 v[20:21], v[20:21], v[172:173], v[218:219] op_sel_hi:[1,0,1]
	v_pk_fma_f32 v[22:23], v[22:23], v[172:173], v[220:221] op_sel_hi:[1,0,1]
	v_pk_fma_f32 v[24:25], v[24:25], v[172:173], v[222:223] op_sel_hi:[1,0,1]
	v_pk_fma_f32 v[26:27], v[26:27], v[172:173], v[224:225] op_sel_hi:[1,0,1]
	v_pk_fma_f32 v[28:29], v[28:29], v[172:173], v[226:227] op_sel_hi:[1,0,1]
	v_pk_fma_f32 v[30:31], v[30:31], v[172:173], v[228:229] op_sel_hi:[1,0,1]
	v_exp_f32_e32 v0, v0
	v_exp_f32_e32 v1, v1
	v_exp_f32_e32 v2, v2
	v_exp_f32_e32 v3, v3
	v_exp_f32_e32 v4, v4
	v_exp_f32_e32 v5, v5
	v_exp_f32_e32 v6, v6
	v_exp_f32_e32 v7, v7
	v_exp_f32_e32 v8, v8
	v_exp_f32_e32 v9, v9
	v_exp_f32_e32 v10, v10
	v_exp_f32_e32 v11, v11
	v_exp_f32_e32 v12, v12
	v_exp_f32_e32 v13, v13
	v_exp_f32_e32 v14, v14
	v_exp_f32_e32 v15, v15
	v_exp_f32_e32 v16, v16
	v_exp_f32_e32 v17, v17
	v_exp_f32_e32 v18, v18
	v_exp_f32_e32 v19, v19
	v_exp_f32_e32 v20, v20
	v_exp_f32_e32 v21, v21
	v_exp_f32_e32 v22, v22
	v_exp_f32_e32 v23, v23
	v_exp_f32_e32 v24, v24
	v_exp_f32_e32 v25, v25
	v_exp_f32_e32 v26, v26
	v_exp_f32_e32 v27, v27
	v_exp_f32_e32 v28, v28
	v_exp_f32_e32 v29, v29
	v_exp_f32_e32 v30, v30
	v_exp_f32_e32 v31, v31
	v_pk_add_f32 v[0:1], v[0:1], 1.0 op_sel_hi:[1,0]
	v_pk_add_f32 v[2:3], v[2:3], 1.0 op_sel_hi:[1,0]
	v_pk_add_f32 v[4:5], v[4:5], 1.0 op_sel_hi:[1,0]
	v_pk_add_f32 v[6:7], v[6:7], 1.0 op_sel_hi:[1,0]
	v_pk_add_f32 v[8:9], v[8:9], 1.0 op_sel_hi:[1,0]
	v_pk_add_f32 v[10:11], v[10:11], 1.0 op_sel_hi:[1,0]
	v_pk_add_f32 v[12:13], v[12:13], 1.0 op_sel_hi:[1,0]
	v_pk_add_f32 v[14:15], v[14:15], 1.0 op_sel_hi:[1,0]
	v_pk_add_f32 v[16:17], v[16:17], 1.0 op_sel_hi:[1,0]
	v_pk_add_f32 v[18:19], v[18:19], 1.0 op_sel_hi:[1,0]
	v_pk_add_f32 v[20:21], v[20:21], 1.0 op_sel_hi:[1,0]
	v_pk_add_f32 v[22:23], v[22:23], 1.0 op_sel_hi:[1,0]
	v_pk_add_f32 v[24:25], v[24:25], 1.0 op_sel_hi:[1,0]
	v_pk_add_f32 v[26:27], v[26:27], 1.0 op_sel_hi:[1,0]
	v_pk_add_f32 v[28:29], v[28:29], 1.0 op_sel_hi:[1,0]
	v_pk_add_f32 v[30:31], v[30:31], 1.0 op_sel_hi:[1,0]
	v_rcp_f32_e32 v0, v0
	v_rcp_f32_e32 v1, v1
	v_rcp_f32_e32 v2, v2
	v_rcp_f32_e32 v3, v3
	v_rcp_f32_e32 v4, v4
	v_rcp_f32_e32 v5, v5
	v_rcp_f32_e32 v6, v6
	v_rcp_f32_e32 v7, v7
	v_rcp_f32_e32 v8, v8
	v_rcp_f32_e32 v9, v9
	v_rcp_f32_e32 v10, v10
	v_rcp_f32_e32 v11, v11
	v_rcp_f32_e32 v12, v12
	v_rcp_f32_e32 v13, v13
	v_rcp_f32_e32 v14, v14
	v_rcp_f32_e32 v15, v15
	v_rcp_f32_e32 v16, v16
	v_rcp_f32_e32 v17, v17
	v_rcp_f32_e32 v18, v18
	v_rcp_f32_e32 v19, v19
	v_rcp_f32_e32 v20, v20
	v_rcp_f32_e32 v21, v21
	v_rcp_f32_e32 v22, v22
	v_rcp_f32_e32 v23, v23
	v_rcp_f32_e32 v24, v24
	v_rcp_f32_e32 v25, v25
	v_rcp_f32_e32 v26, v26
	v_rcp_f32_e32 v27, v27
	v_rcp_f32_e32 v28, v28
	v_rcp_f32_e32 v29, v29
	v_rcp_f32_e32 v30, v30
	v_rcp_f32_e32 v31, v31
	s_nop 0
	v_cvt_pk_bf16_f32 v0, v0, v1
	v_cvt_pk_bf16_f32 v1, v2, v3
	v_cvt_pk_bf16_f32 v2, v4, v5
	v_cvt_pk_bf16_f32 v3, v6, v7
	v_cvt_pk_bf16_f32 v4, v8, v9
	v_cvt_pk_bf16_f32 v5, v10, v11
	v_cvt_pk_bf16_f32 v6, v12, v13
	v_cvt_pk_bf16_f32 v7, v14, v15
	v_cvt_pk_bf16_f32 v16, v16, v17
	v_cvt_pk_bf16_f32 v17, v18, v19
	v_cvt_pk_bf16_f32 v18, v20, v21
	v_cvt_pk_bf16_f32 v19, v22, v23
	v_cvt_pk_bf16_f32 v20, v24, v25
	v_cvt_pk_bf16_f32 v21, v26, v27
	v_cvt_pk_bf16_f32 v22, v28, v29
	v_cvt_pk_bf16_f32 v23, v30, v31
	v_permlane32_swap_b32_e32 v0, v2
	v_permlane32_swap_b32_e32 v1, v3
	v_permlane32_swap_b32_e32 v4, v6
	v_permlane32_swap_b32_e32 v5, v7
	v_permlane32_swap_b32_e32 v16, v18
	v_permlane32_swap_b32_e32 v17, v19
	v_permlane32_swap_b32_e32 v20, v22
	v_permlane32_swap_b32_e32 v21, v23
	global_store_dwordx4 v181, v[0:3], s[74:75] offset:0
	global_store_dwordx4 v181, v[4:7], s[74:75] offset:32
	global_store_dwordx4 v181, v[16:19], s[74:75] offset:64
	global_store_dwordx4 v181, v[20:23], s[74:75] offset:96
	s_add_u32 s74, s74, 0x44000
	s_addc_u32 s75, s75, 0
	v_pk_fma_f32 v[32:33], v[32:33], v[172:173], v[198:199] op_sel:[0,1,0] op_sel_hi:[1,1,1]
	v_pk_fma_f32 v[34:35], v[34:35], v[172:173], v[200:201] op_sel:[0,1,0] op_sel_hi:[1,1,1]
	v_pk_fma_f32 v[36:37], v[36:37], v[172:173], v[202:203] op_sel:[0,1,0] op_sel_hi:[1,1,1]
	v_pk_fma_f32 v[38:39], v[38:39], v[172:173], v[204:205] op_sel:[0,1,0] op_sel_hi:[1,1,1]
	v_pk_fma_f32 v[40:41], v[40:41], v[172:173], v[206:207] op_sel:[0,1,0] op_sel_hi:[1,1,1]
	v_pk_fma_f32 v[42:43], v[42:43], v[172:173], v[208:209] op_sel:[0,1,0] op_sel_hi:[1,1,1]
	v_pk_fma_f32 v[44:45], v[44:45], v[172:173], v[210:211] op_sel:[0,1,0] op_sel_hi:[1,1,1]
	v_pk_fma_f32 v[46:47], v[46:47], v[172:173], v[212:213] op_sel:[0,1,0] op_sel_hi:[1,1,1]
	v_pk_fma_f32 v[48:49], v[48:49], v[172:173], v[214:215] op_sel:[0,1,0] op_sel_hi:[1,1,1]
	v_pk_fma_f32 v[50:51], v[50:51], v[172:173], v[216:217] op_sel:[0,1,0] op_sel_hi:[1,1,1]
	v_pk_fma_f32 v[52:53], v[52:53], v[172:173], v[218:219] op_sel:[0,1,0] op_sel_hi:[1,1,1]
	v_pk_fma_f32 v[54:55], v[54:55], v[172:173], v[220:221] op_sel:[0,1,0] op_sel_hi:[1,1,1]
	v_pk_fma_f32 v[56:57], v[56:57], v[172:173], v[222:223] op_sel:[0,1,0] op_sel_hi:[1,1,1]
	v_pk_fma_f32 v[58:59], v[58:59], v[172:173], v[224:225] op_sel:[0,1,0] op_sel_hi:[1,1,1]
	v_pk_fma_f32 v[60:61], v[60:61], v[172:173], v[226:227] op_sel:[0,1,0] op_sel_hi:[1,1,1]
	v_pk_fma_f32 v[62:63], v[62:63], v[172:173], v[228:229] op_sel:[0,1,0] op_sel_hi:[1,1,1]
	v_exp_f32_e32 v32, v32
	v_exp_f32_e32 v33, v33
	v_exp_f32_e32 v34, v34
	v_exp_f32_e32 v35, v35
	v_exp_f32_e32 v36, v36
	v_exp_f32_e32 v37, v37
	v_exp_f32_e32 v38, v38
	v_exp_f32_e32 v39, v39
	v_exp_f32_e32 v40, v40
	v_exp_f32_e32 v41, v41
	v_exp_f32_e32 v42, v42
	v_exp_f32_e32 v43, v43
	v_exp_f32_e32 v44, v44
	v_exp_f32_e32 v45, v45
	v_exp_f32_e32 v46, v46
	v_exp_f32_e32 v47, v47
	v_exp_f32_e32 v48, v48
	v_exp_f32_e32 v49, v49
	v_exp_f32_e32 v50, v50
	v_exp_f32_e32 v51, v51
	v_exp_f32_e32 v52, v52
	v_exp_f32_e32 v53, v53
	v_exp_f32_e32 v54, v54
	v_exp_f32_e32 v55, v55
	v_exp_f32_e32 v56, v56
	v_exp_f32_e32 v57, v57
	v_exp_f32_e32 v58, v58
	v_exp_f32_e32 v59, v59
	v_exp_f32_e32 v60, v60
	v_exp_f32_e32 v61, v61
	v_exp_f32_e32 v62, v62
	v_exp_f32_e32 v63, v63
	v_pk_add_f32 v[32:33], v[32:33], 1.0 op_sel_hi:[1,0]
	v_pk_add_f32 v[34:35], v[34:35], 1.0 op_sel_hi:[1,0]
	v_pk_add_f32 v[36:37], v[36:37], 1.0 op_sel_hi:[1,0]
	v_pk_add_f32 v[38:39], v[38:39], 1.0 op_sel_hi:[1,0]
	v_pk_add_f32 v[40:41], v[40:41], 1.0 op_sel_hi:[1,0]
	v_pk_add_f32 v[42:43], v[42:43], 1.0 op_sel_hi:[1,0]
	v_pk_add_f32 v[44:45], v[44:45], 1.0 op_sel_hi:[1,0]
	v_pk_add_f32 v[46:47], v[46:47], 1.0 op_sel_hi:[1,0]
	v_pk_add_f32 v[48:49], v[48:49], 1.0 op_sel_hi:[1,0]
	v_pk_add_f32 v[50:51], v[50:51], 1.0 op_sel_hi:[1,0]
	v_pk_add_f32 v[52:53], v[52:53], 1.0 op_sel_hi:[1,0]
	v_pk_add_f32 v[54:55], v[54:55], 1.0 op_sel_hi:[1,0]
	v_pk_add_f32 v[56:57], v[56:57], 1.0 op_sel_hi:[1,0]
	v_pk_add_f32 v[58:59], v[58:59], 1.0 op_sel_hi:[1,0]
	v_pk_add_f32 v[60:61], v[60:61], 1.0 op_sel_hi:[1,0]
	v_pk_add_f32 v[62:63], v[62:63], 1.0 op_sel_hi:[1,0]
	v_rcp_f32_e32 v32, v32
	v_rcp_f32_e32 v33, v33
	v_rcp_f32_e32 v34, v34
	v_rcp_f32_e32 v35, v35
	v_rcp_f32_e32 v36, v36
	v_rcp_f32_e32 v37, v37
	v_rcp_f32_e32 v38, v38
	v_rcp_f32_e32 v39, v39
	v_rcp_f32_e32 v40, v40
	v_rcp_f32_e32 v41, v41
	v_rcp_f32_e32 v42, v42
	v_rcp_f32_e32 v43, v43
	v_rcp_f32_e32 v44, v44
	v_rcp_f32_e32 v45, v45
	v_rcp_f32_e32 v46, v46
	v_rcp_f32_e32 v47, v47
	v_rcp_f32_e32 v48, v48
	v_rcp_f32_e32 v49, v49
	v_rcp_f32_e32 v50, v50
	v_rcp_f32_e32 v51, v51
	v_rcp_f32_e32 v52, v52
	v_rcp_f32_e32 v53, v53
	v_rcp_f32_e32 v54, v54
	v_rcp_f32_e32 v55, v55
	v_rcp_f32_e32 v56, v56
	v_rcp_f32_e32 v57, v57
	v_rcp_f32_e32 v58, v58
	v_rcp_f32_e32 v59, v59
	v_rcp_f32_e32 v60, v60
	v_rcp_f32_e32 v61, v61
	v_rcp_f32_e32 v62, v62
	v_rcp_f32_e32 v63, v63
	s_nop 0
	v_cvt_pk_bf16_f32 v32, v32, v33
	v_cvt_pk_bf16_f32 v33, v34, v35
	v_cvt_pk_bf16_f32 v34, v36, v37
	v_cvt_pk_bf16_f32 v35, v38, v39
	v_cvt_pk_bf16_f32 v36, v40, v41
	v_cvt_pk_bf16_f32 v37, v42, v43
	v_cvt_pk_bf16_f32 v38, v44, v45
	v_cvt_pk_bf16_f32 v39, v46, v47
	v_cvt_pk_bf16_f32 v48, v48, v49
	v_cvt_pk_bf16_f32 v49, v50, v51
	v_cvt_pk_bf16_f32 v50, v52, v53
	v_cvt_pk_bf16_f32 v51, v54, v55
	v_cvt_pk_bf16_f32 v52, v56, v57
	v_cvt_pk_bf16_f32 v53, v58, v59
	v_cvt_pk_bf16_f32 v54, v60, v61
	v_cvt_pk_bf16_f32 v55, v62, v63
	v_permlane32_swap_b32_e32 v32, v34
	v_permlane32_swap_b32_e32 v33, v35
	v_permlane32_swap_b32_e32 v36, v38
	v_permlane32_swap_b32_e32 v37, v39
	v_permlane32_swap_b32_e32 v48, v50
	v_permlane32_swap_b32_e32 v49, v51
	v_permlane32_swap_b32_e32 v52, v54
	v_permlane32_swap_b32_e32 v53, v55
	global_store_dwordx4 v181, v[32:35], s[74:75] offset:0
	global_store_dwordx4 v181, v[36:39], s[74:75] offset:32
	global_store_dwordx4 v181, v[48:51], s[74:75] offset:64
	global_store_dwordx4 v181, v[52:55], s[74:75] offset:96
	s_add_u32 s74, s74, 0x44000
	s_addc_u32 s75, s75, 0
	v_pk_fma_f32 v[64:65], v[64:65], v[174:175], v[198:199] op_sel_hi:[1,0,1]
	v_pk_fma_f32 v[66:67], v[66:67], v[174:175], v[200:201] op_sel_hi:[1,0,1]
	v_pk_fma_f32 v[68:69], v[68:69], v[174:175], v[202:203] op_sel_hi:[1,0,1]
	v_pk_fma_f32 v[70:71], v[70:71], v[174:175], v[204:205] op_sel_hi:[1,0,1]
	v_pk_fma_f32 v[72:73], v[72:73], v[174:175], v[206:207] op_sel_hi:[1,0,1]
	v_pk_fma_f32 v[74:75], v[74:75], v[174:175], v[208:209] op_sel_hi:[1,0,1]
	v_pk_fma_f32 v[76:77], v[76:77], v[174:175], v[210:211] op_sel_hi:[1,0,1]
	v_pk_fma_f32 v[78:79], v[78:79], v[174:175], v[212:213] op_sel_hi:[1,0,1]
	v_pk_fma_f32 v[80:81], v[80:81], v[174:175], v[214:215] op_sel_hi:[1,0,1]
	v_pk_fma_f32 v[82:83], v[82:83], v[174:175], v[216:217] op_sel_hi:[1,0,1]
	v_pk_fma_f32 v[84:85], v[84:85], v[174:175], v[218:219] op_sel_hi:[1,0,1]
	v_pk_fma_f32 v[86:87], v[86:87], v[174:175], v[220:221] op_sel_hi:[1,0,1]
	v_pk_fma_f32 v[88:89], v[88:89], v[174:175], v[222:223] op_sel_hi:[1,0,1]
	v_pk_fma_f32 v[90:91], v[90:91], v[174:175], v[224:225] op_sel_hi:[1,0,1]
	v_pk_fma_f32 v[92:93], v[92:93], v[174:175], v[226:227] op_sel_hi:[1,0,1]
	v_pk_fma_f32 v[94:95], v[94:95], v[174:175], v[228:229] op_sel_hi:[1,0,1]
	v_exp_f32_e32 v64, v64
	v_exp_f32_e32 v65, v65
	v_exp_f32_e32 v66, v66
	v_exp_f32_e32 v67, v67
	v_exp_f32_e32 v68, v68
	v_exp_f32_e32 v69, v69
	v_exp_f32_e32 v70, v70
	v_exp_f32_e32 v71, v71
	v_exp_f32_e32 v72, v72
	v_exp_f32_e32 v73, v73
	v_exp_f32_e32 v74, v74
	v_exp_f32_e32 v75, v75
	v_exp_f32_e32 v76, v76
	v_exp_f32_e32 v77, v77
	v_exp_f32_e32 v78, v78
	v_exp_f32_e32 v79, v79
	v_exp_f32_e32 v80, v80
	v_exp_f32_e32 v81, v81
	v_exp_f32_e32 v82, v82
	v_exp_f32_e32 v83, v83
	v_exp_f32_e32 v84, v84
	v_exp_f32_e32 v85, v85
	v_exp_f32_e32 v86, v86
	v_exp_f32_e32 v87, v87
	v_exp_f32_e32 v88, v88
	v_exp_f32_e32 v89, v89
	v_exp_f32_e32 v90, v90
	v_exp_f32_e32 v91, v91
	v_exp_f32_e32 v92, v92
	v_exp_f32_e32 v93, v93
	v_exp_f32_e32 v94, v94
	v_exp_f32_e32 v95, v95
	v_pk_add_f32 v[64:65], v[64:65], 1.0 op_sel_hi:[1,0]
	v_pk_add_f32 v[66:67], v[66:67], 1.0 op_sel_hi:[1,0]
	v_pk_add_f32 v[68:69], v[68:69], 1.0 op_sel_hi:[1,0]
	v_pk_add_f32 v[70:71], v[70:71], 1.0 op_sel_hi:[1,0]
	v_pk_add_f32 v[72:73], v[72:73], 1.0 op_sel_hi:[1,0]
	v_pk_add_f32 v[74:75], v[74:75], 1.0 op_sel_hi:[1,0]
	v_pk_add_f32 v[76:77], v[76:77], 1.0 op_sel_hi:[1,0]
	v_pk_add_f32 v[78:79], v[78:79], 1.0 op_sel_hi:[1,0]
	v_pk_add_f32 v[80:81], v[80:81], 1.0 op_sel_hi:[1,0]
	v_pk_add_f32 v[82:83], v[82:83], 1.0 op_sel_hi:[1,0]
	v_pk_add_f32 v[84:85], v[84:85], 1.0 op_sel_hi:[1,0]
	v_pk_add_f32 v[86:87], v[86:87], 1.0 op_sel_hi:[1,0]
	v_pk_add_f32 v[88:89], v[88:89], 1.0 op_sel_hi:[1,0]
	v_pk_add_f32 v[90:91], v[90:91], 1.0 op_sel_hi:[1,0]
	v_pk_add_f32 v[92:93], v[92:93], 1.0 op_sel_hi:[1,0]
	v_pk_add_f32 v[94:95], v[94:95], 1.0 op_sel_hi:[1,0]
	v_rcp_f32_e32 v64, v64
	v_rcp_f32_e32 v65, v65
	v_rcp_f32_e32 v66, v66
	v_rcp_f32_e32 v67, v67
	v_rcp_f32_e32 v68, v68
	v_rcp_f32_e32 v69, v69
	v_rcp_f32_e32 v70, v70
	v_rcp_f32_e32 v71, v71
	v_rcp_f32_e32 v72, v72
	v_rcp_f32_e32 v73, v73
	v_rcp_f32_e32 v74, v74
	v_rcp_f32_e32 v75, v75
	v_rcp_f32_e32 v76, v76
	v_rcp_f32_e32 v77, v77
	v_rcp_f32_e32 v78, v78
	v_rcp_f32_e32 v79, v79
	v_rcp_f32_e32 v80, v80
	v_rcp_f32_e32 v81, v81
	v_rcp_f32_e32 v82, v82
	v_rcp_f32_e32 v83, v83
	v_rcp_f32_e32 v84, v84
	v_rcp_f32_e32 v85, v85
	v_rcp_f32_e32 v86, v86
	v_rcp_f32_e32 v87, v87
	v_rcp_f32_e32 v88, v88
	v_rcp_f32_e32 v89, v89
	v_rcp_f32_e32 v90, v90
	v_rcp_f32_e32 v91, v91
	v_rcp_f32_e32 v92, v92
	v_rcp_f32_e32 v93, v93
	v_rcp_f32_e32 v94, v94
	v_rcp_f32_e32 v95, v95
	s_nop 0
	v_cvt_pk_bf16_f32 v64, v64, v65
	v_cvt_pk_bf16_f32 v65, v66, v67
	v_cvt_pk_bf16_f32 v66, v68, v69
	v_cvt_pk_bf16_f32 v67, v70, v71
	v_cvt_pk_bf16_f32 v68, v72, v73
	v_cvt_pk_bf16_f32 v69, v74, v75
	v_cvt_pk_bf16_f32 v70, v76, v77
	v_cvt_pk_bf16_f32 v71, v78, v79
	v_cvt_pk_bf16_f32 v80, v80, v81
	v_cvt_pk_bf16_f32 v81, v82, v83
	v_cvt_pk_bf16_f32 v82, v84, v85
	v_cvt_pk_bf16_f32 v83, v86, v87
	v_cvt_pk_bf16_f32 v84, v88, v89
	v_cvt_pk_bf16_f32 v85, v90, v91
	v_cvt_pk_bf16_f32 v86, v92, v93
	v_cvt_pk_bf16_f32 v87, v94, v95
	v_permlane32_swap_b32_e32 v64, v66
	v_permlane32_swap_b32_e32 v65, v67
	v_permlane32_swap_b32_e32 v68, v70
	v_permlane32_swap_b32_e32 v69, v71
	v_permlane32_swap_b32_e32 v80, v82
	v_permlane32_swap_b32_e32 v81, v83
	v_permlane32_swap_b32_e32 v84, v86
	v_permlane32_swap_b32_e32 v85, v87
	global_store_dwordx4 v181, v[64:67], s[74:75] offset:0
	global_store_dwordx4 v181, v[68:71], s[74:75] offset:32
	global_store_dwordx4 v181, v[80:83], s[74:75] offset:64
	global_store_dwordx4 v181, v[84:87], s[74:75] offset:96
	s_add_u32 s74, s74, 0x44000
	s_addc_u32 s75, s75, 0
	v_pk_fma_f32 v[96:97], v[96:97], v[174:175], v[198:199] op_sel:[0,1,0] op_sel_hi:[1,1,1]
	v_pk_fma_f32 v[98:99], v[98:99], v[174:175], v[200:201] op_sel:[0,1,0] op_sel_hi:[1,1,1]
	v_pk_fma_f32 v[100:101], v[100:101], v[174:175], v[202:203] op_sel:[0,1,0] op_sel_hi:[1,1,1]
	v_pk_fma_f32 v[102:103], v[102:103], v[174:175], v[204:205] op_sel:[0,1,0] op_sel_hi:[1,1,1]
	v_pk_fma_f32 v[104:105], v[104:105], v[174:175], v[206:207] op_sel:[0,1,0] op_sel_hi:[1,1,1]
	v_pk_fma_f32 v[106:107], v[106:107], v[174:175], v[208:209] op_sel:[0,1,0] op_sel_hi:[1,1,1]
	v_pk_fma_f32 v[108:109], v[108:109], v[174:175], v[210:211] op_sel:[0,1,0] op_sel_hi:[1,1,1]
	v_pk_fma_f32 v[110:111], v[110:111], v[174:175], v[212:213] op_sel:[0,1,0] op_sel_hi:[1,1,1]
	v_pk_fma_f32 v[112:113], v[112:113], v[174:175], v[214:215] op_sel:[0,1,0] op_sel_hi:[1,1,1]
	v_pk_fma_f32 v[114:115], v[114:115], v[174:175], v[216:217] op_sel:[0,1,0] op_sel_hi:[1,1,1]
	v_pk_fma_f32 v[116:117], v[116:117], v[174:175], v[218:219] op_sel:[0,1,0] op_sel_hi:[1,1,1]
	v_pk_fma_f32 v[118:119], v[118:119], v[174:175], v[220:221] op_sel:[0,1,0] op_sel_hi:[1,1,1]
	v_pk_fma_f32 v[120:121], v[120:121], v[174:175], v[222:223] op_sel:[0,1,0] op_sel_hi:[1,1,1]
	v_pk_fma_f32 v[122:123], v[122:123], v[174:175], v[224:225] op_sel:[0,1,0] op_sel_hi:[1,1,1]
	v_pk_fma_f32 v[124:125], v[124:125], v[174:175], v[226:227] op_sel:[0,1,0] op_sel_hi:[1,1,1]
	v_pk_fma_f32 v[126:127], v[126:127], v[174:175], v[228:229] op_sel:[0,1,0] op_sel_hi:[1,1,1]
	v_exp_f32_e32 v96, v96
	v_exp_f32_e32 v97, v97
	v_exp_f32_e32 v98, v98
	v_exp_f32_e32 v99, v99
	v_exp_f32_e32 v100, v100
	v_exp_f32_e32 v101, v101
	v_exp_f32_e32 v102, v102
	v_exp_f32_e32 v103, v103
	v_exp_f32_e32 v104, v104
	v_exp_f32_e32 v105, v105
	v_exp_f32_e32 v106, v106
	v_exp_f32_e32 v107, v107
	v_exp_f32_e32 v108, v108
	v_exp_f32_e32 v109, v109
	v_exp_f32_e32 v110, v110
	v_exp_f32_e32 v111, v111
	v_exp_f32_e32 v112, v112
	v_exp_f32_e32 v113, v113
	v_exp_f32_e32 v114, v114
	v_exp_f32_e32 v115, v115
	v_exp_f32_e32 v116, v116
	v_exp_f32_e32 v117, v117
	v_exp_f32_e32 v118, v118
	v_exp_f32_e32 v119, v119
	v_exp_f32_e32 v120, v120
	v_exp_f32_e32 v121, v121
	v_exp_f32_e32 v122, v122
	v_exp_f32_e32 v123, v123
	v_exp_f32_e32 v124, v124
	v_exp_f32_e32 v125, v125
	v_exp_f32_e32 v126, v126
	v_exp_f32_e32 v127, v127
	v_pk_add_f32 v[96:97], v[96:97], 1.0 op_sel_hi:[1,0]
	v_pk_add_f32 v[98:99], v[98:99], 1.0 op_sel_hi:[1,0]
	v_pk_add_f32 v[100:101], v[100:101], 1.0 op_sel_hi:[1,0]
	v_pk_add_f32 v[102:103], v[102:103], 1.0 op_sel_hi:[1,0]
	v_pk_add_f32 v[104:105], v[104:105], 1.0 op_sel_hi:[1,0]
	v_pk_add_f32 v[106:107], v[106:107], 1.0 op_sel_hi:[1,0]
	v_pk_add_f32 v[108:109], v[108:109], 1.0 op_sel_hi:[1,0]
	v_pk_add_f32 v[110:111], v[110:111], 1.0 op_sel_hi:[1,0]
	v_pk_add_f32 v[112:113], v[112:113], 1.0 op_sel_hi:[1,0]
	v_pk_add_f32 v[114:115], v[114:115], 1.0 op_sel_hi:[1,0]
	v_pk_add_f32 v[116:117], v[116:117], 1.0 op_sel_hi:[1,0]
	v_pk_add_f32 v[118:119], v[118:119], 1.0 op_sel_hi:[1,0]
	v_pk_add_f32 v[120:121], v[120:121], 1.0 op_sel_hi:[1,0]
	v_pk_add_f32 v[122:123], v[122:123], 1.0 op_sel_hi:[1,0]
	v_pk_add_f32 v[124:125], v[124:125], 1.0 op_sel_hi:[1,0]
	v_pk_add_f32 v[126:127], v[126:127], 1.0 op_sel_hi:[1,0]
	v_rcp_f32_e32 v96, v96
	v_rcp_f32_e32 v97, v97
	v_rcp_f32_e32 v98, v98
	v_rcp_f32_e32 v99, v99
	v_rcp_f32_e32 v100, v100
	v_rcp_f32_e32 v101, v101
	v_rcp_f32_e32 v102, v102
	v_rcp_f32_e32 v103, v103
	v_rcp_f32_e32 v104, v104
	v_rcp_f32_e32 v105, v105
	v_rcp_f32_e32 v106, v106
	v_rcp_f32_e32 v107, v107
	v_rcp_f32_e32 v108, v108
	v_rcp_f32_e32 v109, v109
	v_rcp_f32_e32 v110, v110
	v_rcp_f32_e32 v111, v111
	v_rcp_f32_e32 v112, v112
	v_rcp_f32_e32 v113, v113
	v_rcp_f32_e32 v114, v114
	v_rcp_f32_e32 v115, v115
	v_rcp_f32_e32 v116, v116
	v_rcp_f32_e32 v117, v117
	v_rcp_f32_e32 v118, v118
	v_rcp_f32_e32 v119, v119
	v_rcp_f32_e32 v120, v120
	v_rcp_f32_e32 v121, v121
	v_rcp_f32_e32 v122, v122
	v_rcp_f32_e32 v123, v123
	v_rcp_f32_e32 v124, v124
	v_rcp_f32_e32 v125, v125
	v_rcp_f32_e32 v126, v126
	v_rcp_f32_e32 v127, v127
	s_nop 0
	v_cvt_pk_bf16_f32 v96, v96, v97
	v_cvt_pk_bf16_f32 v97, v98, v99
	v_cvt_pk_bf16_f32 v98, v100, v101
	v_cvt_pk_bf16_f32 v99, v102, v103
	v_cvt_pk_bf16_f32 v100, v104, v105
	v_cvt_pk_bf16_f32 v101, v106, v107
	v_cvt_pk_bf16_f32 v102, v108, v109
	v_cvt_pk_bf16_f32 v103, v110, v111
	v_cvt_pk_bf16_f32 v112, v112, v113
	v_cvt_pk_bf16_f32 v113, v114, v115
	v_cvt_pk_bf16_f32 v114, v116, v117
	v_cvt_pk_bf16_f32 v115, v118, v119
	v_cvt_pk_bf16_f32 v116, v120, v121
	v_cvt_pk_bf16_f32 v117, v122, v123
	v_cvt_pk_bf16_f32 v118, v124, v125
	v_cvt_pk_bf16_f32 v119, v126, v127
	v_permlane32_swap_b32_e32 v96, v98
	v_permlane32_swap_b32_e32 v97, v99
	v_permlane32_swap_b32_e32 v100, v102
	v_permlane32_swap_b32_e32 v101, v103
	v_permlane32_swap_b32_e32 v112, v114
	v_permlane32_swap_b32_e32 v113, v115
	v_permlane32_swap_b32_e32 v116, v118
	v_permlane32_swap_b32_e32 v117, v119
	global_store_dwordx4 v181, v[96:99], s[74:75] offset:0
	global_store_dwordx4 v181, v[100:103], s[74:75] offset:32
	global_store_dwordx4 v181, v[112:115], s[74:75] offset:64
	global_store_dwordx4 v181, v[116:119], s[74:75] offset:96
	s_branch .Lpe_ret_L1
.Lpe_vt_L1:
	s_lshl_b32 s35, s34, 2
	s_add_u32 s35, s35, s28
	s_add_u32 s36, s28, 6
	s_cmp_eq_u32 s25, 8
	s_cselect_b32 s35, s36, s35
	s_lshr_b32 s36, s29, 11
	s_mul_i32 s36, s36, 10
	s_add_u32 s36, s36, s35
	s_lshl_b32 s36, s36, 18
	s_and_b32 s37, s29, 0x7ff
	s_lshl_b32 s37, s37, 1
	s_add_u32 s36, s36, s37
	s_add_u32 s38, s72, 0x14920000
	s_addc_u32 s39, s73, 0
	s_add_u32 s38, s38, s36
	s_addc_u32 s39, s39, 0
	s_mul_i32 s36, s26, 10240
	s_add_u32 s36, s36, 0x10000
	v_lshlrev_b32_e32 v180, 1, v197
	v_mul_u32_u24_e32 v181, 36, v146
	v_add3_u32 v180, v180, v181, s36
	v_lshrrev_b32_e32 v181, 3, v179
	v_and_b32_e32 v146, 7, v179
	v_lshlrev_b32_e32 v146, 4, v146
	v_mul_u32_u24_e32 v198, 144, v181
	v_add3_u32 v198, v198, v146, s36
	v_lshl_add_u32 v199, v181, 12, v146
	s_waitcnt vmcnt(0)
	v_mov_b32_e32 v197, 0x358637bd
	v_pk_add_f32 v[128:129], v[128:129], v[130:131]
	v_pk_add_f32 v[132:133], v[132:133], v[134:135]
	v_pk_add_f32 v[136:137], v[136:137], v[138:139]
	v_pk_add_f32 v[140:141], v[140:141], v[142:143]
	v_pk_add_f32 v[164:165], v[164:165], v[166:167]
	v_pk_add_f32 v[168:169], v[168:169], v[170:171]
	v_pk_add_f32 v[246:247], v[246:247], v[248:249]
	v_pk_add_f32 v[250:251], v[250:251], v[252:253]
	v_pk_add_f32 v[128:129], v[128:129], v[132:133]
	v_pk_add_f32 v[136:137], v[136:137], v[140:141]
	v_pk_add_f32 v[164:165], v[164:165], v[168:169]
	v_pk_add_f32 v[246:247], v[246:247], v[250:251]
	v_add_f32_e32 v128, v128, v129
	v_add_f32_e32 v136, v136, v137
	v_add_f32_e32 v164, v164, v165
	v_add_f32_e32 v246, v246, v247
	v_fmamk_f32 v128, v128, 0x3a800000, v197
	v_fmamk_f32 v136, v136, 0x3a800000, v197
	v_fmamk_f32 v164, v164, 0x3a800000, v197
	v_fmamk_f32 v246, v246, 0x3a800000, v197
	v_rsq_f32_e32 v172, v128
	v_rsq_f32_e32 v173, v136
	v_rsq_f32_e32 v174, v164
	v_rsq_f32_e32 v175, v246
	s_nop 0
	s_add_u32 s76, s99, s90
	s_cmp_lt_u32 s76, 0x440
	s_cselect_b32 s80, 1, 0
	s_cselect_b32 s83, 0x200000, 0
	s_lshl_b32 s76, s24, 19
	s_lshl_b32 s77, s26, 16
	s_add_u32 s76, s76, s77
	s_and_b32 s77, s24, 7
	s_lshl_b32 s77, s77, 8
	s_add_u32 s76, s76, s77
	s_add_u32 s78, s72, 0xa120000
	s_addc_u32 s79, s73, 0
	s_add_u32 s78, s78, s76
	s_addc_u32 s79, s79, 0
	s_lshl_b32 s76, s25, 19
	s_add_u32 s76, s76, s83
	s_add_u32 s76, s76, s77
	s_lshl_b32 s77, s26, 16
	s_add_u32 s76, s76, s77
	s_add_u32 s82, s72, 0x880000
	s_addc_u32 s83, s73, 0
	s_add_u32 s82, s82, s76
	s_addc_u32 s83, s83, 0
	s_lshl_b32 s76, s26, 12
	s_add_u32 s76, s76, s56
	s_mov_b32 m0, s76
	s_nop 0
	global_load_lds_dwordx4 v177, s[78:79]
	s_add_u32 s78, s78, 0x4000
	s_addc_u32 s79, s79, 0
	s_add_u32 s76, s76, 0x400
	s_mov_b32 m0, s76
	s_nop 0
	global_load_lds_dwordx4 v185, s[78:79]
	s_add_u32 s78, s78, 0x4000
	s_addc_u32 s79, s79, 0
	s_add_u32 s76, s76, 0x400
	s_mov_b32 m0, s76
	s_nop 0
	global_load_lds_dwordx4 v177, s[78:79]
	s_add_u32 s78, s78, 0x4000
	s_addc_u32 s79, s79, 0
	s_add_u32 s76, s76, 0x400
	s_mov_b32 m0, s76
	s_nop 0
	global_load_lds_dwordx4 v185, s[78:79]
	s_add_u32 s78, s78, 0x4000
	s_addc_u32 s79, s79, 0
	s_add_u32 s76, s76, 0x400
	s_sub_u32 s76, s76, s56
	s_add_u32 s76, s76, 0x7000
	s_mov_b32 m0, s76
	s_nop 0
	global_load_lds_dwordx4 v177, s[82:83]
	s_add_u32 s82, s82, 0x4000
	s_addc_u32 s83, s83, 0
	s_add_u32 s76, s76, 0x400
	s_mov_b32 m0, s76
	s_nop 0
	global_load_lds_dwordx4 v185, s[82:83]
	s_add_u32 s82, s82, 0x4000
	s_addc_u32 s83, s83, 0
	s_add_u32 s76, s76, 0x400
	s_mov_b32 m0, s76
	s_nop 0
	global_load_lds_dwordx4 v177, s[82:83]
	s_add_u32 s82, s82, 0x4000
	s_addc_u32 s83, s83, 0
	s_add_u32 s76, s76, 0x400
	s_mov_b32 m0, s76
	s_nop 0
	global_load_lds_dwordx4 v185, s[82:83]
	s_add_u32 s82, s82, 0x4000
	s_addc_u32 s83, s83, 0
	s_add_u32 s76, s76, 0x400
	v_pk_mul_f32 v[0:1], v[0:1], v[172:173] op_sel_hi:[1,0]
	v_pk_mul_f32 v[2:3], v[2:3], v[172:173] op_sel_hi:[1,0]
	v_pk_mul_f32 v[4:5], v[4:5], v[172:173] op_sel_hi:[1,0]
	v_pk_mul_f32 v[6:7], v[6:7], v[172:173] op_sel_hi:[1,0]
	v_pk_mul_f32 v[8:9], v[8:9], v[172:173] op_sel_hi:[1,0]
	v_pk_mul_f32 v[10:11], v[10:11], v[172:173] op_sel_hi:[1,0]
	v_pk_mul_f32 v[12:13], v[12:13], v[172:173] op_sel_hi:[1,0]
	v_pk_mul_f32 v[14:15], v[14:15], v[172:173] op_sel_hi:[1,0]
	v_pk_mul_f32 v[16:17], v[16:17], v[172:173] op_sel_hi:[1,0]
	v_pk_mul_f32 v[18:19], v[18:19], v[172:173] op_sel_hi:[1,0]
	v_pk_mul_f32 v[20:21], v[20:21], v[172:173] op_sel_hi:[1,0]
	v_pk_mul_f32 v[22:23], v[22:23], v[172:173] op_sel_hi:[1,0]
	v_pk_mul_f32 v[24:25], v[24:25], v[172:173] op_sel_hi:[1,0]
	v_pk_mul_f32 v[26:27], v[26:27], v[172:173] op_sel_hi:[1,0]
	v_pk_mul_f32 v[28:29], v[28:29], v[172:173] op_sel_hi:[1,0]
	v_pk_mul_f32 v[30:31], v[30:31], v[172:173] op_sel_hi:[1,0]
	v_pk_mul_f32 v[32:33], v[32:33], v[172:173] op_sel:[0,1] op_sel_hi:[1,1]
	v_pk_mul_f32 v[34:35], v[34:35], v[172:173] op_sel:[0,1] op_sel_hi:[1,1]
	v_pk_mul_f32 v[36:37], v[36:37], v[172:173] op_sel:[0,1] op_sel_hi:[1,1]
	v_pk_mul_f32 v[38:39], v[38:39], v[172:173] op_sel:[0,1] op_sel_hi:[1,1]
	v_pk_mul_f32 v[40:41], v[40:41], v[172:173] op_sel:[0,1] op_sel_hi:[1,1]
	v_pk_mul_f32 v[42:43], v[42:43], v[172:173] op_sel:[0,1] op_sel_hi:[1,1]
	v_pk_mul_f32 v[44:45], v[44:45], v[172:173] op_sel:[0,1] op_sel_hi:[1,1]
	v_pk_mul_f32 v[46:47], v[46:47], v[172:173] op_sel:[0,1] op_sel_hi:[1,1]
	v_pk_mul_f32 v[48:49], v[48:49], v[172:173] op_sel:[0,1] op_sel_hi:[1,1]
	v_pk_mul_f32 v[50:51], v[50:51], v[172:173] op_sel:[0,1] op_sel_hi:[1,1]
	v_pk_mul_f32 v[52:53], v[52:53], v[172:173] op_sel:[0,1] op_sel_hi:[1,1]
	v_pk_mul_f32 v[54:55], v[54:55], v[172:173] op_sel:[0,1] op_sel_hi:[1,1]
	v_pk_mul_f32 v[56:57], v[56:57], v[172:173] op_sel:[0,1] op_sel_hi:[1,1]
	v_pk_mul_f32 v[58:59], v[58:59], v[172:173] op_sel:[0,1] op_sel_hi:[1,1]
	v_pk_mul_f32 v[60:61], v[60:61], v[172:173] op_sel:[0,1] op_sel_hi:[1,1]
	v_pk_mul_f32 v[62:63], v[62:63], v[172:173] op_sel:[0,1] op_sel_hi:[1,1]
	v_pk_mul_f32 v[64:65], v[64:65], v[174:175] op_sel_hi:[1,0]
	v_pk_mul_f32 v[66:67], v[66:67], v[174:175] op_sel_hi:[1,0]
	v_pk_mul_f32 v[68:69], v[68:69], v[174:175] op_sel_hi:[1,0]
	v_pk_mul_f32 v[70:71], v[70:71], v[174:175] op_sel_hi:[1,0]
	v_pk_mul_f32 v[72:73], v[72:73], v[174:175] op_sel_hi:[1,0]
	v_pk_mul_f32 v[74:75], v[74:75], v[174:175] op_sel_hi:[1,0]
	v_pk_mul_f32 v[76:77], v[76:77], v[174:175] op_sel_hi:[1,0]
	v_pk_mul_f32 v[78:79], v[78:79], v[174:175] op_sel_hi:[1,0]
	v_pk_mul_f32 v[80:81], v[80:81], v[174:175] op_sel_hi:[1,0]
	v_pk_mul_f32 v[82:83], v[82:83], v[174:175] op_sel_hi:[1,0]
	v_pk_mul_f32 v[84:85], v[84:85], v[174:175] op_sel_hi:[1,0]
	v_pk_mul_f32 v[86:87], v[86:87], v[174:175] op_sel_hi:[1,0]
	v_pk_mul_f32 v[88:89], v[88:89], v[174:175] op_sel_hi:[1,0]
	v_pk_mul_f32 v[90:91], v[90:91], v[174:175] op_sel_hi:[1,0]
	v_pk_mul_f32 v[92:93], v[92:93], v[174:175] op_sel_hi:[1,0]
	v_pk_mul_f32 v[94:95], v[94:95], v[174:175] op_sel_hi:[1,0]
	v_pk_mul_f32 v[96:97], v[96:97], v[174:175] op_sel:[0,1] op_sel_hi:[1,1]
	v_pk_mul_f32 v[98:99], v[98:99], v[174:175] op_sel:[0,1] op_sel_hi:[1,1]
	v_pk_mul_f32 v[100:101], v[100:101], v[174:175] op_sel:[0,1] op_sel_hi:[1,1]
	v_pk_mul_f32 v[102:103], v[102:103], v[174:175] op_sel:[0,1] op_sel_hi:[1,1]
	v_pk_mul_f32 v[104:105], v[104:105], v[174:175] op_sel:[0,1] op_sel_hi:[1,1]
	v_pk_mul_f32 v[106:107], v[106:107], v[174:175] op_sel:[0,1] op_sel_hi:[1,1]
	v_pk_mul_f32 v[108:109], v[108:109], v[174:175] op_sel:[0,1] op_sel_hi:[1,1]
	v_pk_mul_f32 v[110:111], v[110:111], v[174:175] op_sel:[0,1] op_sel_hi:[1,1]
	v_pk_mul_f32 v[112:113], v[112:113], v[174:175] op_sel:[0,1] op_sel_hi:[1,1]
	v_pk_mul_f32 v[114:115], v[114:115], v[174:175] op_sel:[0,1] op_sel_hi:[1,1]
	v_pk_mul_f32 v[116:117], v[116:117], v[174:175] op_sel:[0,1] op_sel_hi:[1,1]
	v_pk_mul_f32 v[118:119], v[118:119], v[174:175] op_sel:[0,1] op_sel_hi:[1,1]
	v_pk_mul_f32 v[120:121], v[120:121], v[174:175] op_sel:[0,1] op_sel_hi:[1,1]
	v_pk_mul_f32 v[122:123], v[122:123], v[174:175] op_sel:[0,1] op_sel_hi:[1,1]
	v_pk_mul_f32 v[124:125], v[124:125], v[174:175] op_sel:[0,1] op_sel_hi:[1,1]
	v_pk_mul_f32 v[126:127], v[126:127], v[174:175] op_sel:[0,1] op_sel_hi:[1,1]
	v_cvt_pk_bf16_f32 v0, v0, v1
	v_cvt_pk_bf16_f32 v1, v2, v3
	v_cvt_pk_bf16_f32 v2, v4, v5
	v_cvt_pk_bf16_f32 v3, v6, v7
	v_cvt_pk_bf16_f32 v4, v8, v9
	v_cvt_pk_bf16_f32 v5, v10, v11
	v_cvt_pk_bf16_f32 v6, v12, v13
	v_cvt_pk_bf16_f32 v7, v14, v15
	ds_write_b16 v180, v0 offset:0
	ds_write_b16_d16_hi v180, v0 offset:144
	ds_write_b16 v180, v1 offset:288
	ds_write_b16_d16_hi v180, v1 offset:432
	ds_write_b16 v180, v2 offset:1152
	ds_write_b16_d16_hi v180, v2 offset:1296
	ds_write_b16 v180, v3 offset:1440
	ds_write_b16_d16_hi v180, v3 offset:1584
	ds_write_b16 v180, v4 offset:2304
	ds_write_b16_d16_hi v180, v4 offset:2448
	ds_write_b16 v180, v5 offset:2592
	ds_write_b16_d16_hi v180, v5 offset:2736
	ds_write_b16 v180, v6 offset:3456
	ds_write_b16_d16_hi v180, v6 offset:3600
	ds_write_b16 v180, v7 offset:3744
	ds_write_b16_d16_hi v180, v7 offset:3888
	v_cvt_pk_bf16_f32 v16, v16, v17
	v_cvt_pk_bf16_f32 v17, v18, v19
	v_cvt_pk_bf16_f32 v18, v20, v21
	v_cvt_pk_bf16_f32 v19, v22, v23
	v_cvt_pk_bf16_f32 v20, v24, v25
	v_cvt_pk_bf16_f32 v21, v26, v27
	v_cvt_pk_bf16_f32 v22, v28, v29
	v_cvt_pk_bf16_f32 v23, v30, v31
	ds_write_b16 v180, v16 offset:4608
	ds_write_b16_d16_hi v180, v16 offset:4752
	ds_write_b16 v180, v17 offset:4896
	ds_write_b16_d16_hi v180, v17 offset:5040
	ds_write_b16 v180, v18 offset:5760
	ds_write_b16_d16_hi v180, v18 offset:5904
	ds_write_b16 v180, v19 offset:6048
	ds_write_b16_d16_hi v180, v19 offset:6192
	ds_write_b16 v180, v20 offset:6912
	ds_write_b16_d16_hi v180, v20 offset:7056
	ds_write_b16 v180, v21 offset:7200
	ds_write_b16_d16_hi v180, v21 offset:7344
	ds_write_b16 v180, v22 offset:8064
	ds_write_b16_d16_hi v180, v22 offset:8208
	ds_write_b16 v180, v23 offset:8352
	ds_write_b16_d16_hi v180, v23 offset:8496
	v_cvt_pk_bf16_f32 v32, v32, v33
	v_cvt_pk_bf16_f32 v33, v34, v35
	v_cvt_pk_bf16_f32 v34, v36, v37
	v_cvt_pk_bf16_f32 v35, v38, v39
	v_cvt_pk_bf16_f32 v36, v40, v41
	v_cvt_pk_bf16_f32 v37, v42, v43
	v_cvt_pk_bf16_f32 v38, v44, v45
	v_cvt_pk_bf16_f32 v39, v46, v47
	ds_write_b16 v180, v32 offset:64
	ds_write_b16_d16_hi v180, v32 offset:208
	ds_write_b16 v180, v33 offset:352
	ds_write_b16_d16_hi v180, v33 offset:496
	ds_write_b16 v180, v34 offset:1216
	ds_write_b16_d16_hi v180, v34 offset:1360
	ds_write_b16 v180, v35 offset:1504
	ds_write_b16_d16_hi v180, v35 offset:1648
	ds_write_b16 v180, v36 offset:2368
	ds_write_b16_d16_hi v180, v36 offset:2512
	ds_write_b16 v180, v37 offset:2656
	ds_write_b16_d16_hi v180, v37 offset:2800
	ds_write_b16 v180, v38 offset:3520
	ds_write_b16_d16_hi v180, v38 offset:3664
	ds_write_b16 v180, v39 offset:3808
	ds_write_b16_d16_hi v180, v39 offset:3952
	v_cvt_pk_bf16_f32 v48, v48, v49
	v_cvt_pk_bf16_f32 v49, v50, v51
	v_cvt_pk_bf16_f32 v50, v52, v53
	v_cvt_pk_bf16_f32 v51, v54, v55
	v_cvt_pk_bf16_f32 v52, v56, v57
	v_cvt_pk_bf16_f32 v53, v58, v59
	v_cvt_pk_bf16_f32 v54, v60, v61
	v_cvt_pk_bf16_f32 v55, v62, v63
	ds_write_b16 v180, v48 offset:4672
	ds_write_b16_d16_hi v180, v48 offset:4816
	ds_write_b16 v180, v49 offset:4960
	ds_write_b16_d16_hi v180, v49 offset:5104
	ds_write_b16 v180, v50 offset:5824
	ds_write_b16_d16_hi v180, v50 offset:5968
	ds_write_b16 v180, v51 offset:6112
	ds_write_b16_d16_hi v180, v51 offset:6256
	ds_write_b16 v180, v52 offset:6976
	ds_write_b16_d16_hi v180, v52 offset:7120
	ds_write_b16 v180, v53 offset:7264
	ds_write_b16_d16_hi v180, v53 offset:7408
	ds_write_b16 v180, v54 offset:8128
	ds_write_b16_d16_hi v180, v54 offset:8272
	ds_write_b16 v180, v55 offset:8416
	ds_write_b16_d16_hi v180, v55 offset:8560
	s_waitcnt lgkmcnt(0)
	ds_read_b128 v[0:3], v198 offset:0
	ds_read_b128 v[4:7], v198 offset:1152
	ds_read_b128 v[8:11], v198 offset:2304
	ds_read_b128 v[12:15], v198 offset:3456
	ds_read_b128 v[16:19], v198 offset:4608
	ds_read_b128 v[20:23], v198 offset:5760
	ds_read_b128 v[24:27], v198 offset:6912
	ds_read_b128 v[28:31], v198 offset:8064
	s_waitcnt lgkmcnt(7)
	global_store_dwordx4 v199, v[0:3], s[38:39]
	s_add_u32 s38, s38, 0x8000
	s_addc_u32 s39, s39, 0
	s_waitcnt lgkmcnt(6)
	global_store_dwordx4 v199, v[4:7], s[38:39]
	s_add_u32 s38, s38, 0x8000
	s_addc_u32 s39, s39, 0
	s_waitcnt lgkmcnt(5)
	global_store_dwordx4 v199, v[8:11], s[38:39]
	s_add_u32 s38, s38, 0x8000
	s_addc_u32 s39, s39, 0
	s_waitcnt lgkmcnt(4)
	global_store_dwordx4 v199, v[12:15], s[38:39]
	s_add_u32 s38, s38, 0x8000
	s_addc_u32 s39, s39, 0
	s_waitcnt lgkmcnt(3)
	global_store_dwordx4 v199, v[16:19], s[38:39]
	s_add_u32 s38, s38, 0x8000
	s_addc_u32 s39, s39, 0
	s_waitcnt lgkmcnt(2)
	global_store_dwordx4 v199, v[20:23], s[38:39]
	s_add_u32 s38, s38, 0x8000
	s_addc_u32 s39, s39, 0
	s_waitcnt lgkmcnt(1)
	global_store_dwordx4 v199, v[24:27], s[38:39]
	s_add_u32 s38, s38, 0x8000
	s_addc_u32 s39, s39, 0
	s_waitcnt lgkmcnt(0)
	global_store_dwordx4 v199, v[28:31], s[38:39]
	s_sub_u32 s38, s38, 229248
	s_subb_u32 s39, s39, 0
	v_cvt_pk_bf16_f32 v64, v64, v65
	v_cvt_pk_bf16_f32 v65, v66, v67
	v_cvt_pk_bf16_f32 v66, v68, v69
	v_cvt_pk_bf16_f32 v67, v70, v71
	v_cvt_pk_bf16_f32 v68, v72, v73
	v_cvt_pk_bf16_f32 v69, v74, v75
	v_cvt_pk_bf16_f32 v70, v76, v77
	v_cvt_pk_bf16_f32 v71, v78, v79
	ds_write_b16 v180, v64 offset:0
	ds_write_b16_d16_hi v180, v64 offset:144
	ds_write_b16 v180, v65 offset:288
	ds_write_b16_d16_hi v180, v65 offset:432
	ds_write_b16 v180, v66 offset:1152
	ds_write_b16_d16_hi v180, v66 offset:1296
	ds_write_b16 v180, v67 offset:1440
	ds_write_b16_d16_hi v180, v67 offset:1584
	ds_write_b16 v180, v68 offset:2304
	ds_write_b16_d16_hi v180, v68 offset:2448
	ds_write_b16 v180, v69 offset:2592
	ds_write_b16_d16_hi v180, v69 offset:2736
	ds_write_b16 v180, v70 offset:3456
	ds_write_b16_d16_hi v180, v70 offset:3600
	ds_write_b16 v180, v71 offset:3744
	ds_write_b16_d16_hi v180, v71 offset:3888
	v_cvt_pk_bf16_f32 v80, v80, v81
	v_cvt_pk_bf16_f32 v81, v82, v83
	v_cvt_pk_bf16_f32 v82, v84, v85
	v_cvt_pk_bf16_f32 v83, v86, v87
	v_cvt_pk_bf16_f32 v84, v88, v89
	v_cvt_pk_bf16_f32 v85, v90, v91
	v_cvt_pk_bf16_f32 v86, v92, v93
	v_cvt_pk_bf16_f32 v87, v94, v95
	ds_write_b16 v180, v80 offset:4608
	ds_write_b16_d16_hi v180, v80 offset:4752
	ds_write_b16 v180, v81 offset:4896
	ds_write_b16_d16_hi v180, v81 offset:5040
	ds_write_b16 v180, v82 offset:5760
	ds_write_b16_d16_hi v180, v82 offset:5904
	ds_write_b16 v180, v83 offset:6048
	ds_write_b16_d16_hi v180, v83 offset:6192
	ds_write_b16 v180, v84 offset:6912
	ds_write_b16_d16_hi v180, v84 offset:7056
	ds_write_b16 v180, v85 offset:7200
	ds_write_b16_d16_hi v180, v85 offset:7344
	ds_write_b16 v180, v86 offset:8064
	ds_write_b16_d16_hi v180, v86 offset:8208
	ds_write_b16 v180, v87 offset:8352
	ds_write_b16_d16_hi v180, v87 offset:8496
	v_cvt_pk_bf16_f32 v96, v96, v97
	v_cvt_pk_bf16_f32 v97, v98, v99
	v_cvt_pk_bf16_f32 v98, v100, v101
	v_cvt_pk_bf16_f32 v99, v102, v103
	v_cvt_pk_bf16_f32 v100, v104, v105
	v_cvt_pk_bf16_f32 v101, v106, v107
	v_cvt_pk_bf16_f32 v102, v108, v109
	v_cvt_pk_bf16_f32 v103, v110, v111
	ds_write_b16 v180, v96 offset:64
	ds_write_b16_d16_hi v180, v96 offset:208
	ds_write_b16 v180, v97 offset:352
	ds_write_b16_d16_hi v180, v97 offset:496
	ds_write_b16 v180, v98 offset:1216
	ds_write_b16_d16_hi v180, v98 offset:1360
	ds_write_b16 v180, v99 offset:1504
	ds_write_b16_d16_hi v180, v99 offset:1648
	ds_write_b16 v180, v100 offset:2368
	ds_write_b16_d16_hi v180, v100 offset:2512
	ds_write_b16 v180, v101 offset:2656
	ds_write_b16_d16_hi v180, v101 offset:2800
	ds_write_b16 v180, v102 offset:3520
	ds_write_b16_d16_hi v180, v102 offset:3664
	ds_write_b16 v180, v103 offset:3808
	ds_write_b16_d16_hi v180, v103 offset:3952
	v_cvt_pk_bf16_f32 v112, v112, v113
	v_cvt_pk_bf16_f32 v113, v114, v115
	v_cvt_pk_bf16_f32 v114, v116, v117
	v_cvt_pk_bf16_f32 v115, v118, v119
	v_cvt_pk_bf16_f32 v116, v120, v121
	v_cvt_pk_bf16_f32 v117, v122, v123
	v_cvt_pk_bf16_f32 v118, v124, v125
	v_cvt_pk_bf16_f32 v119, v126, v127
	ds_write_b16 v180, v112 offset:4672
	ds_write_b16_d16_hi v180, v112 offset:4816
	ds_write_b16 v180, v113 offset:4960
	ds_write_b16_d16_hi v180, v113 offset:5104
	ds_write_b16 v180, v114 offset:5824
	ds_write_b16_d16_hi v180, v114 offset:5968
	ds_write_b16 v180, v115 offset:6112
	ds_write_b16_d16_hi v180, v115 offset:6256
	ds_write_b16 v180, v116 offset:6976
	ds_write_b16_d16_hi v180, v116 offset:7120
	ds_write_b16 v180, v117 offset:7264
	ds_write_b16_d16_hi v180, v117 offset:7408
	ds_write_b16 v180, v118 offset:8128
	ds_write_b16_d16_hi v180, v118 offset:8272
	ds_write_b16 v180, v119 offset:8416
	ds_write_b16_d16_hi v180, v119 offset:8560
	s_waitcnt lgkmcnt(0)
	ds_read_b128 v[64:67], v198 offset:0
	ds_read_b128 v[68:71], v198 offset:1152
	ds_read_b128 v[72:75], v198 offset:2304
	ds_read_b128 v[76:79], v198 offset:3456
	ds_read_b128 v[80:83], v198 offset:4608
	ds_read_b128 v[84:87], v198 offset:5760
	ds_read_b128 v[88:91], v198 offset:6912
	ds_read_b128 v[92:95], v198 offset:8064
	s_waitcnt lgkmcnt(7)
	global_store_dwordx4 v199, v[64:67], s[38:39]
	s_add_u32 s38, s38, 0x8000
	s_addc_u32 s39, s39, 0
	s_waitcnt lgkmcnt(6)
	global_store_dwordx4 v199, v[68:71], s[38:39]
	s_add_u32 s38, s38, 0x8000
	s_addc_u32 s39, s39, 0
	s_waitcnt lgkmcnt(5)
	global_store_dwordx4 v199, v[72:75], s[38:39]
	s_add_u32 s38, s38, 0x8000
	s_addc_u32 s39, s39, 0
	s_waitcnt lgkmcnt(4)
	global_store_dwordx4 v199, v[76:79], s[38:39]
	s_add_u32 s38, s38, 0x8000
	s_addc_u32 s39, s39, 0
	s_waitcnt lgkmcnt(3)
	global_store_dwordx4 v199, v[80:83], s[38:39]
	s_add_u32 s38, s38, 0x8000
	s_addc_u32 s39, s39, 0
	s_waitcnt lgkmcnt(2)
	global_store_dwordx4 v199, v[84:87], s[38:39]
	s_add_u32 s38, s38, 0x8000
	s_addc_u32 s39, s39, 0
	s_waitcnt lgkmcnt(1)
	global_store_dwordx4 v199, v[88:91], s[38:39]
	s_add_u32 s38, s38, 0x8000
	s_addc_u32 s39, s39, 0
	s_waitcnt lgkmcnt(0)
	global_store_dwordx4 v199, v[92:95], s[38:39]

	.amdhsa_kernel _Z11mega_kernel6Params
		.amdhsa_group_segment_fixed_size 163840
		.amdhsa_private_segment_fixed_size 0
		.amdhsa_kernarg_size 408
		.amdhsa_user_sgpr_count 2
		.amdhsa_user_sgpr_dispatch_ptr 0
		.amdhsa_user_sgpr_queue_ptr 0
		.amdhsa_user_sgpr_kernarg_segment_ptr 1
		.amdhsa_user_sgpr_dispatch_id 0
		.amdhsa_user_sgpr_kernarg_preload_length 0
		.amdhsa_user_sgpr_kernarg_preload_offset 0
		.amdhsa_user_sgpr_private_segment_size 0
		.amdhsa_uses_dynamic_stack 0
		.amdhsa_enable_private_segment 0
		.amdhsa_system_sgpr_workgroup_id_x 1
		.amdhsa_system_sgpr_workgroup_id_y 0
		.amdhsa_system_sgpr_workgroup_id_z 0
		.amdhsa_system_sgpr_workgroup_info 0
		.amdhsa_system_vgpr_workitem_id 2
		.amdhsa_next_free_vgpr 256
		.amdhsa_next_free_sgpr 102
		.amdhsa_accum_offset 256
		.amdhsa_reserve_vcc 1
		.amdhsa_float_round_mode_32 0
		.amdhsa_float_round_mode_16_64 0
		.amdhsa_float_denorm_mode_32 3
		.amdhsa_float_denorm_mode_16_64 3
		.amdhsa_dx10_clamp 1
		.amdhsa_ieee_mode 1
		.amdhsa_fp16_overflow 0
		.amdhsa_tg_split 0
		.amdhsa_exception_fp_ieee_invalid_op 0
		.amdhsa_exception_fp_denorm_src 0
		.amdhsa_exception_fp_ieee_div_zero 0
		.amdhsa_exception_fp_ieee_overflow 0
		.amdhsa_exception_fp_ieee_underflow 0
		.amdhsa_exception_fp_ieee_inexact 0
		.amdhsa_exception_int_div_zero 0
	.end_amdhsa_kernel

amdhsa.kernels:
  - .agpr_count:     0
    .args:
      - .offset:         0
        .size:           152
        .value_kind:     by_value
      - .offset:         152
        .size:           4
        .value_kind:     hidden_block_count_x
      - .offset:         156
        .size:           4
        .value_kind:     hidden_block_count_y
      - .offset:         160
        .size:           4
        .value_kind:     hidden_block_count_z
      - .offset:         164
        .size:           2
        .value_kind:     hidden_group_size_x
      - .offset:         166
        .size:           2
        .value_kind:     hidden_group_size_y
      - .offset:         168
        .size:           2
        .value_kind:     hidden_group_size_z
      - .offset:         170
        .size:           2
        .value_kind:     hidden_remainder_x
      - .offset:         172
        .size:           2
        .value_kind:     hidden_remainder_y
      - .offset:         174
        .size:           2
        .value_kind:     hidden_remainder_z
      - .offset:         192
        .size:           8
        .value_kind:     hidden_global_offset_x
      - .offset:         200
        .size:           8
        .value_kind:     hidden_global_offset_y
      - .offset:         208
        .size:           8
        .value_kind:     hidden_global_offset_z
      - .offset:         216
        .size:           2
        .value_kind:     hidden_grid_dims
      - .offset:         240
        .size:           8
        .value_kind:     hidden_multigrid_sync_arg
    .group_segment_fixed_size: 163840
    .kernarg_segment_align: 8
    .kernarg_segment_size: 408
    .language:       OpenCL C
    .language_version:
      - 2
      - 0
    .max_flat_workgroup_size: 512
    .name:           _Z11mega_kernel6Params
    .private_segment_fixed_size: 0
    .sgpr_count:     108
    .sgpr_spill_count: 89
    .symbol:         _Z11mega_kernel6Params.kd
    .uniform_work_group_size: 1
    .uses_dynamic_stack: false
    .vgpr_count:     256
    .vgpr_spill_count: 0
    .wavefront_size: 64
